# phase-1 norm_mod_rows rewritten straight-line with x prefetched two rows ahead and counted waits (removes the load/wait/store ladder); plus gnw ladder, in-proj L1 rowsq hoist
# speedup vs baseline: 1.0080x; 1.0080x over previous
.LBB0_100:
	s_mov_b32 s5, 0
	v_readlane_b32 s0, v253, 10
	v_readlane_b32 s1, v253, 11
	s_lshl_b64 s[16:17], s[4:5], 12
	s_add_u32 s0, s0, s16
	s_addc_u32 s1, s1, s17
	v_readlane_b32 s10, v253, 27
	v_readlane_b32 s11, v253, 28
	s_add_u32 s12, s10, 0x1000
	s_addc_u32 s13, s11, 0
	s_lshl_b64 s[14:15], s[4:5], 11
	s_add_u32 s14, s62, s14
	s_addc_u32 s15, s63, s15
	s_add_u32 s14, s14, 0x6200000
	s_addc_u32 s15, s15, 0
	v_mov_b32_e32 v149, 0
	global_load_dwordx4 v[100:103], v56, s[10:11]
	global_load_dwordx4 v[104:107], v56, s[10:11] offset:1024
	global_load_dwordx4 v[108:111], v56, s[10:11] offset:2048
	global_load_dwordx4 v[112:115], v56, s[10:11] offset:3072
	global_load_dwordx4 v[84:87], v56, s[12:13]
	global_load_dwordx4 v[88:91], v56, s[12:13] offset:1024
	global_load_dwordx4 v[92:95], v56, s[12:13] offset:2048
	global_load_dwordx4 v[96:99], v56, s[12:13] offset:3072
	s_add_u32 s10, s10, 0x6000
	s_addc_u32 s11, s11, 0
	s_add_u32 s12, s12, 0x6000
	s_addc_u32 s13, s13, 0
	global_load_dwordx4 v[16:19], v56, s[0:1] nt
	global_load_dwordx4 v[20:23], v56, s[0:1] offset:1024 nt
	global_load_dwordx4 v[24:27], v56, s[0:1] offset:2048 nt
	global_load_dwordx4 v[28:31], v56, s[0:1] offset:3072 nt
	s_add_u32 s0, s0, 0x800000
	s_addc_u32 s1, s1, 0
	global_load_dwordx4 v[32:35], v56, s[0:1] nt
	global_load_dwordx4 v[36:39], v56, s[0:1] offset:1024 nt
	global_load_dwordx4 v[40:43], v56, s[0:1] offset:2048 nt
	global_load_dwordx4 v[44:47], v56, s[0:1] offset:3072 nt
	s_add_u32 s0, s0, 0x800000
	s_addc_u32 s1, s1, 0
	global_load_dwordx4 v[68:71], v56, s[0:1] nt
	global_load_dwordx4 v[72:75], v56, s[0:1] offset:1024 nt
	global_load_dwordx4 v[76:79], v56, s[0:1] offset:2048 nt
	global_load_dwordx4 v[80:83], v56, s[0:1] offset:3072 nt
	s_add_u32 s0, s0, 0x800000
	s_addc_u32 s1, s1, 0
	global_load_dwordx4 v[132:135], v56, s[10:11]
	global_load_dwordx4 v[136:139], v56, s[10:11] offset:1024
	global_load_dwordx4 v[140:143], v56, s[10:11] offset:2048
	global_load_dwordx4 v[144:147], v56, s[10:11] offset:3072
	global_load_dwordx4 v[116:119], v56, s[12:13]
	global_load_dwordx4 v[120:123], v56, s[12:13] offset:1024
	global_load_dwordx4 v[124:127], v56, s[12:13] offset:2048
	global_load_dwordx4 v[128:131], v56, s[12:13] offset:3072
	s_add_u32 s10, s10, 0x6000
	s_addc_u32 s11, s11, 0
	s_add_u32 s12, s12, 0x6000
	s_addc_u32 s13, s13, 0
	s_waitcnt vmcnt(16)
	v_pk_mul_f32 v[58:59], v[16:17], v[16:17]
	v_pk_fma_f32 v[58:59], v[18:19], v[18:19], v[58:59]
	v_pk_fma_f32 v[58:59], v[20:21], v[20:21], v[58:59]
	v_pk_fma_f32 v[58:59], v[22:23], v[22:23], v[58:59]
	v_pk_fma_f32 v[58:59], v[24:25], v[24:25], v[58:59]
	v_pk_fma_f32 v[58:59], v[26:27], v[26:27], v[58:59]
	v_pk_fma_f32 v[58:59], v[28:29], v[28:29], v[58:59]
	v_pk_fma_f32 v[58:59], v[30:31], v[30:31], v[58:59]
	v_add_f32_e32 v60, v58, v59
	s_nop 1
	v_add_f32_dpp v61, v60, v60 quad_perm:[1,0,3,2] row_mask:0xf bank_mask:0xf
	s_nop 1
	v_add_f32_dpp v60, v61, v61 quad_perm:[2,3,0,1] row_mask:0xf bank_mask:0xf
	s_nop 1
	v_add_f32_dpp v61, v60, v60 row_half_mirror row_mask:0xf bank_mask:0xf
	s_nop 1
	v_add_f32_dpp v60, v61, v61 row_mirror row_mask:0xf bank_mask:0xf
	v_mov_b32_e32 v61, v60
	s_nop 1
	v_add_f32_dpp v61, v60, v60 row_bcast:15 row_mask:0xa bank_mask:0xf
	s_nop 1
	v_mov_b32_e32 v60, v61
	s_nop 1
	v_add_f32_dpp v60, v61, v61 row_bcast:31 row_mask:0xc bank_mask:0xf
	s_nop 1
	v_readlane_b32 s16, v60, 63
	s_nop 1
	v_mov_b32_e32 v148, s16
	v_fmamk_f32 v148, v148, 0x3a800000, v66
	v_rsq_f32_e32 v148, v148
	s_nop 0
	s_waitcnt vmcnt(20)
	v_pk_mul_f32 v[16:17], v[16:17], v[148:149] op_sel_hi:[1,0]
	v_pk_mul_f32 v[18:19], v[18:19], v[148:149] op_sel_hi:[1,0]
	v_pk_add_f32 v[84:85], v[84:85], 1.0 op_sel_hi:[1,0]
	v_pk_add_f32 v[86:87], v[86:87], 1.0 op_sel_hi:[1,0]
	v_pk_mul_f32 v[16:17], v[0:1], v[16:17]
	v_pk_mul_f32 v[18:19], v[2:3], v[18:19]
	v_pk_fma_f32 v[16:17], v[16:17], v[84:85], v[100:101]
	v_pk_fma_f32 v[18:19], v[18:19], v[86:87], v[102:103]
	v_cvt_pk_bf16_f32 v16, v16, v17
	v_cvt_pk_bf16_f32 v17, v18, v19
	global_store_dwordx2 v48, v[16:17], s[14:15]
	v_pk_mul_f32 v[20:21], v[20:21], v[148:149] op_sel_hi:[1,0]
	v_pk_mul_f32 v[22:23], v[22:23], v[148:149] op_sel_hi:[1,0]
	v_pk_add_f32 v[88:89], v[88:89], 1.0 op_sel_hi:[1,0]
	v_pk_add_f32 v[90:91], v[90:91], 1.0 op_sel_hi:[1,0]
	v_pk_mul_f32 v[20:21], v[4:5], v[20:21]
	v_pk_mul_f32 v[22:23], v[6:7], v[22:23]
	v_pk_fma_f32 v[20:21], v[20:21], v[88:89], v[104:105]
	v_pk_fma_f32 v[22:23], v[22:23], v[90:91], v[106:107]
	v_cvt_pk_bf16_f32 v20, v20, v21
	v_cvt_pk_bf16_f32 v21, v22, v23
	global_store_dwordx2 v48, v[20:21], s[14:15] offset:512
	v_pk_mul_f32 v[24:25], v[24:25], v[148:149] op_sel_hi:[1,0]
	v_pk_mul_f32 v[26:27], v[26:27], v[148:149] op_sel_hi:[1,0]
	v_pk_add_f32 v[92:93], v[92:93], 1.0 op_sel_hi:[1,0]
	v_pk_add_f32 v[94:95], v[94:95], 1.0 op_sel_hi:[1,0]
	v_pk_mul_f32 v[24:25], v[8:9], v[24:25]
	v_pk_mul_f32 v[26:27], v[10:11], v[26:27]
	v_pk_fma_f32 v[24:25], v[24:25], v[92:93], v[108:109]
	v_pk_fma_f32 v[26:27], v[26:27], v[94:95], v[110:111]
	v_cvt_pk_bf16_f32 v24, v24, v25
	v_cvt_pk_bf16_f32 v25, v26, v27
	global_store_dwordx2 v48, v[24:25], s[14:15] offset:1024
	v_pk_mul_f32 v[28:29], v[28:29], v[148:149] op_sel_hi:[1,0]
	v_pk_mul_f32 v[30:31], v[30:31], v[148:149] op_sel_hi:[1,0]
	v_pk_add_f32 v[96:97], v[96:97], 1.0 op_sel_hi:[1,0]
	v_pk_add_f32 v[98:99], v[98:99], 1.0 op_sel_hi:[1,0]
	v_pk_mul_f32 v[28:29], v[12:13], v[28:29]
	v_pk_mul_f32 v[30:31], v[14:15], v[30:31]
	v_pk_fma_f32 v[28:29], v[28:29], v[96:97], v[112:113]
	v_pk_fma_f32 v[30:31], v[30:31], v[98:99], v[114:115]
	v_cvt_pk_bf16_f32 v28, v28, v29
	v_cvt_pk_bf16_f32 v29, v30, v31
	global_store_dwordx2 v48, v[28:29], s[14:15] offset:1536
	s_add_u32 s14, s14, 0x400000
	s_addc_u32 s15, s15, 0
	global_load_dwordx4 v[16:19], v56, s[0:1] nt
	global_load_dwordx4 v[20:23], v56, s[0:1] offset:1024 nt
	global_load_dwordx4 v[24:27], v56, s[0:1] offset:2048 nt
	global_load_dwordx4 v[28:31], v56, s[0:1] offset:3072 nt
	s_add_u32 s0, s0, 0x800000
	s_addc_u32 s1, s1, 0
	global_load_dwordx4 v[100:103], v56, s[10:11]
	global_load_dwordx4 v[104:107], v56, s[10:11] offset:1024
	global_load_dwordx4 v[108:111], v56, s[10:11] offset:2048
	global_load_dwordx4 v[112:115], v56, s[10:11] offset:3072
	global_load_dwordx4 v[84:87], v56, s[12:13]
	global_load_dwordx4 v[88:91], v56, s[12:13] offset:1024
	global_load_dwordx4 v[92:95], v56, s[12:13] offset:2048
	global_load_dwordx4 v[96:99], v56, s[12:13] offset:3072
	s_add_u32 s10, s10, 0x6000
	s_addc_u32 s11, s11, 0
	s_add_u32 s12, s12, 0x6000
	s_addc_u32 s13, s13, 0
	s_waitcnt vmcnt(28)
	v_pk_mul_f32 v[58:59], v[32:33], v[32:33]
	v_pk_fma_f32 v[58:59], v[34:35], v[34:35], v[58:59]
	v_pk_fma_f32 v[58:59], v[36:37], v[36:37], v[58:59]
	v_pk_fma_f32 v[58:59], v[38:39], v[38:39], v[58:59]
	v_pk_fma_f32 v[58:59], v[40:41], v[40:41], v[58:59]
	v_pk_fma_f32 v[58:59], v[42:43], v[42:43], v[58:59]
	v_pk_fma_f32 v[58:59], v[44:45], v[44:45], v[58:59]
	v_pk_fma_f32 v[58:59], v[46:47], v[46:47], v[58:59]
	v_add_f32_e32 v60, v58, v59
	s_nop 1
	v_add_f32_dpp v61, v60, v60 quad_perm:[1,0,3,2] row_mask:0xf bank_mask:0xf
	s_nop 1
	v_add_f32_dpp v60, v61, v61 quad_perm:[2,3,0,1] row_mask:0xf bank_mask:0xf
	s_nop 1
	v_add_f32_dpp v61, v60, v60 row_half_mirror row_mask:0xf bank_mask:0xf
	s_nop 1
	v_add_f32_dpp v60, v61, v61 row_mirror row_mask:0xf bank_mask:0xf
	v_mov_b32_e32 v61, v60
	s_nop 1
	v_add_f32_dpp v61, v60, v60 row_bcast:15 row_mask:0xa bank_mask:0xf
	s_nop 1
	v_mov_b32_e32 v60, v61
	s_nop 1
	v_add_f32_dpp v60, v61, v61 row_bcast:31 row_mask:0xc bank_mask:0xf
	s_nop 1
	v_readlane_b32 s16, v60, 63
	s_nop 1
	v_mov_b32_e32 v148, s16
	v_fmamk_f32 v148, v148, 0x3a800000, v66
	v_rsq_f32_e32 v148, v148
	s_nop 0
	s_waitcnt vmcnt(16)
	v_pk_mul_f32 v[32:33], v[32:33], v[148:149] op_sel_hi:[1,0]
	v_pk_mul_f32 v[34:35], v[34:35], v[148:149] op_sel_hi:[1,0]
	v_pk_add_f32 v[116:117], v[116:117], 1.0 op_sel_hi:[1,0]
	v_pk_add_f32 v[118:119], v[118:119], 1.0 op_sel_hi:[1,0]
	v_pk_mul_f32 v[32:33], v[0:1], v[32:33]
	v_pk_mul_f32 v[34:35], v[2:3], v[34:35]
	v_pk_fma_f32 v[32:33], v[32:33], v[116:117], v[132:133]
	v_pk_fma_f32 v[34:35], v[34:35], v[118:119], v[134:135]
	v_cvt_pk_bf16_f32 v32, v32, v33
	v_cvt_pk_bf16_f32 v33, v34, v35
	global_store_dwordx2 v48, v[32:33], s[14:15]
	v_pk_mul_f32 v[36:37], v[36:37], v[148:149] op_sel_hi:[1,0]
	v_pk_mul_f32 v[38:39], v[38:39], v[148:149] op_sel_hi:[1,0]
	v_pk_add_f32 v[120:121], v[120:121], 1.0 op_sel_hi:[1,0]
	v_pk_add_f32 v[122:123], v[122:123], 1.0 op_sel_hi:[1,0]
	v_pk_mul_f32 v[36:37], v[4:5], v[36:37]
	v_pk_mul_f32 v[38:39], v[6:7], v[38:39]
	v_pk_fma_f32 v[36:37], v[36:37], v[120:121], v[136:137]
	v_pk_fma_f32 v[38:39], v[38:39], v[122:123], v[138:139]
	v_cvt_pk_bf16_f32 v36, v36, v37
	v_cvt_pk_bf16_f32 v37, v38, v39
	global_store_dwordx2 v48, v[36:37], s[14:15] offset:512
	v_pk_mul_f32 v[40:41], v[40:41], v[148:149] op_sel_hi:[1,0]
	v_pk_mul_f32 v[42:43], v[42:43], v[148:149] op_sel_hi:[1,0]
	v_pk_add_f32 v[124:125], v[124:125], 1.0 op_sel_hi:[1,0]
	v_pk_add_f32 v[126:127], v[126:127], 1.0 op_sel_hi:[1,0]
	v_pk_mul_f32 v[40:41], v[8:9], v[40:41]
	v_pk_mul_f32 v[42:43], v[10:11], v[42:43]
	v_pk_fma_f32 v[40:41], v[40:41], v[124:125], v[140:141]
	v_pk_fma_f32 v[42:43], v[42:43], v[126:127], v[142:143]
	v_cvt_pk_bf16_f32 v40, v40, v41
	v_cvt_pk_bf16_f32 v41, v42, v43
	global_store_dwordx2 v48, v[40:41], s[14:15] offset:1024
	v_pk_mul_f32 v[44:45], v[44:45], v[148:149] op_sel_hi:[1,0]
	v_pk_mul_f32 v[46:47], v[46:47], v[148:149] op_sel_hi:[1,0]
	v_pk_add_f32 v[128:129], v[128:129], 1.0 op_sel_hi:[1,0]
	v_pk_add_f32 v[130:131], v[130:131], 1.0 op_sel_hi:[1,0]
	v_pk_mul_f32 v[44:45], v[12:13], v[44:45]
	v_pk_mul_f32 v[46:47], v[14:15], v[46:47]
	v_pk_fma_f32 v[44:45], v[44:45], v[128:129], v[144:145]
	v_pk_fma_f32 v[46:47], v[46:47], v[130:131], v[146:147]
	v_cvt_pk_bf16_f32 v44, v44, v45
	v_cvt_pk_bf16_f32 v45, v46, v47
	global_store_dwordx2 v48, v[44:45], s[14:15] offset:1536
	s_add_u32 s14, s14, 0x400000
	s_addc_u32 s15, s15, 0
	global_load_dwordx4 v[32:35], v56, s[0:1] nt
	global_load_dwordx4 v[36:39], v56, s[0:1] offset:1024 nt
	global_load_dwordx4 v[40:43], v56, s[0:1] offset:2048 nt
	global_load_dwordx4 v[44:47], v56, s[0:1] offset:3072 nt
	s_add_u32 s0, s0, 0x800000
	s_addc_u32 s1, s1, 0
	global_load_dwordx4 v[132:135], v56, s[10:11]
	global_load_dwordx4 v[136:139], v56, s[10:11] offset:1024
	global_load_dwordx4 v[140:143], v56, s[10:11] offset:2048
	global_load_dwordx4 v[144:147], v56, s[10:11] offset:3072
	global_load_dwordx4 v[116:119], v56, s[12:13]
	global_load_dwordx4 v[120:123], v56, s[12:13] offset:1024
	global_load_dwordx4 v[124:127], v56, s[12:13] offset:2048
	global_load_dwordx4 v[128:131], v56, s[12:13] offset:3072
	s_add_u32 s10, s10, 0x6000
	s_addc_u32 s11, s11, 0
	s_add_u32 s12, s12, 0x6000
	s_addc_u32 s13, s13, 0
	s_waitcnt vmcnt(40)
	v_pk_mul_f32 v[58:59], v[68:69], v[68:69]
	v_pk_fma_f32 v[58:59], v[70:71], v[70:71], v[58:59]
	v_pk_fma_f32 v[58:59], v[72:73], v[72:73], v[58:59]
	v_pk_fma_f32 v[58:59], v[74:75], v[74:75], v[58:59]
	v_pk_fma_f32 v[58:59], v[76:77], v[76:77], v[58:59]
	v_pk_fma_f32 v[58:59], v[78:79], v[78:79], v[58:59]
	v_pk_fma_f32 v[58:59], v[80:81], v[80:81], v[58:59]
	v_pk_fma_f32 v[58:59], v[82:83], v[82:83], v[58:59]
	v_add_f32_e32 v60, v58, v59
	s_nop 1
	v_add_f32_dpp v61, v60, v60 quad_perm:[1,0,3,2] row_mask:0xf bank_mask:0xf
	s_nop 1
	v_add_f32_dpp v60, v61, v61 quad_perm:[2,3,0,1] row_mask:0xf bank_mask:0xf
	s_nop 1
	v_add_f32_dpp v61, v60, v60 row_half_mirror row_mask:0xf bank_mask:0xf
	s_nop 1
	v_add_f32_dpp v60, v61, v61 row_mirror row_mask:0xf bank_mask:0xf
	v_mov_b32_e32 v61, v60
	s_nop 1
	v_add_f32_dpp v61, v60, v60 row_bcast:15 row_mask:0xa bank_mask:0xf
	s_nop 1
	v_mov_b32_e32 v60, v61
	s_nop 1
	v_add_f32_dpp v60, v61, v61 row_bcast:31 row_mask:0xc bank_mask:0xf
	s_nop 1
	v_readlane_b32 s16, v60, 63
	s_nop 1
	v_mov_b32_e32 v148, s16
	v_fmamk_f32 v148, v148, 0x3a800000, v66
	v_rsq_f32_e32 v148, v148
	s_nop 0
	s_waitcnt vmcnt(16)
	v_pk_mul_f32 v[68:69], v[68:69], v[148:149] op_sel_hi:[1,0]
	v_pk_mul_f32 v[70:71], v[70:71], v[148:149] op_sel_hi:[1,0]
	v_pk_add_f32 v[84:85], v[84:85], 1.0 op_sel_hi:[1,0]
	v_pk_add_f32 v[86:87], v[86:87], 1.0 op_sel_hi:[1,0]
	v_pk_mul_f32 v[68:69], v[0:1], v[68:69]
	v_pk_mul_f32 v[70:71], v[2:3], v[70:71]
	v_pk_fma_f32 v[68:69], v[68:69], v[84:85], v[100:101]
	v_pk_fma_f32 v[70:71], v[70:71], v[86:87], v[102:103]
	v_cvt_pk_bf16_f32 v68, v68, v69
	v_cvt_pk_bf16_f32 v69, v70, v71
	global_store_dwordx2 v48, v[68:69], s[14:15]
	v_pk_mul_f32 v[72:73], v[72:73], v[148:149] op_sel_hi:[1,0]
	v_pk_mul_f32 v[74:75], v[74:75], v[148:149] op_sel_hi:[1,0]
	v_pk_add_f32 v[88:89], v[88:89], 1.0 op_sel_hi:[1,0]
	v_pk_add_f32 v[90:91], v[90:91], 1.0 op_sel_hi:[1,0]
	v_pk_mul_f32 v[72:73], v[4:5], v[72:73]
	v_pk_mul_f32 v[74:75], v[6:7], v[74:75]
	v_pk_fma_f32 v[72:73], v[72:73], v[88:89], v[104:105]
	v_pk_fma_f32 v[74:75], v[74:75], v[90:91], v[106:107]
	v_cvt_pk_bf16_f32 v72, v72, v73
	v_cvt_pk_bf16_f32 v73, v74, v75
	global_store_dwordx2 v48, v[72:73], s[14:15] offset:512
	v_pk_mul_f32 v[76:77], v[76:77], v[148:149] op_sel_hi:[1,0]
	v_pk_mul_f32 v[78:79], v[78:79], v[148:149] op_sel_hi:[1,0]
	v_pk_add_f32 v[92:93], v[92:93], 1.0 op_sel_hi:[1,0]
	v_pk_add_f32 v[94:95], v[94:95], 1.0 op_sel_hi:[1,0]
	v_pk_mul_f32 v[76:77], v[8:9], v[76:77]
	v_pk_mul_f32 v[78:79], v[10:11], v[78:79]
	v_pk_fma_f32 v[76:77], v[76:77], v[92:93], v[108:109]
	v_pk_fma_f32 v[78:79], v[78:79], v[94:95], v[110:111]
	v_cvt_pk_bf16_f32 v76, v76, v77
	v_cvt_pk_bf16_f32 v77, v78, v79
	global_store_dwordx2 v48, v[76:77], s[14:15] offset:1024
	v_pk_mul_f32 v[80:81], v[80:81], v[148:149] op_sel_hi:[1,0]
	v_pk_mul_f32 v[82:83], v[82:83], v[148:149] op_sel_hi:[1,0]
	v_pk_add_f32 v[96:97], v[96:97], 1.0 op_sel_hi:[1,0]
	v_pk_add_f32 v[98:99], v[98:99], 1.0 op_sel_hi:[1,0]
	v_pk_mul_f32 v[80:81], v[12:13], v[80:81]
	v_pk_mul_f32 v[82:83], v[14:15], v[82:83]
	v_pk_fma_f32 v[80:81], v[80:81], v[96:97], v[112:113]
	v_pk_fma_f32 v[82:83], v[82:83], v[98:99], v[114:115]
	v_cvt_pk_bf16_f32 v80, v80, v81
	v_cvt_pk_bf16_f32 v81, v82, v83
	global_store_dwordx2 v48, v[80:81], s[14:15] offset:1536
	s_add_u32 s14, s14, 0x400000
	s_addc_u32 s15, s15, 0
	global_load_dwordx4 v[68:71], v56, s[0:1] nt
	global_load_dwordx4 v[72:75], v56, s[0:1] offset:1024 nt
	global_load_dwordx4 v[76:79], v56, s[0:1] offset:2048 nt
	global_load_dwordx4 v[80:83], v56, s[0:1] offset:3072 nt
	s_add_u32 s0, s0, 0x800000
	s_addc_u32 s1, s1, 0
	global_load_dwordx4 v[100:103], v56, s[10:11]
	global_load_dwordx4 v[104:107], v56, s[10:11] offset:1024
	global_load_dwordx4 v[108:111], v56, s[10:11] offset:2048
	global_load_dwordx4 v[112:115], v56, s[10:11] offset:3072
	global_load_dwordx4 v[84:87], v56, s[12:13]
	global_load_dwordx4 v[88:91], v56, s[12:13] offset:1024
	global_load_dwordx4 v[92:95], v56, s[12:13] offset:2048
	global_load_dwordx4 v[96:99], v56, s[12:13] offset:3072
	s_add_u32 s10, s10, 0x6000
	s_addc_u32 s11, s11, 0
	s_add_u32 s12, s12, 0x6000
	s_addc_u32 s13, s13, 0
	s_waitcnt vmcnt(40)
	v_pk_mul_f32 v[58:59], v[16:17], v[16:17]
	v_pk_fma_f32 v[58:59], v[18:19], v[18:19], v[58:59]
	v_pk_fma_f32 v[58:59], v[20:21], v[20:21], v[58:59]
	v_pk_fma_f32 v[58:59], v[22:23], v[22:23], v[58:59]
	v_pk_fma_f32 v[58:59], v[24:25], v[24:25], v[58:59]
	v_pk_fma_f32 v[58:59], v[26:27], v[26:27], v[58:59]
	v_pk_fma_f32 v[58:59], v[28:29], v[28:29], v[58:59]
	v_pk_fma_f32 v[58:59], v[30:31], v[30:31], v[58:59]
	v_add_f32_e32 v60, v58, v59
	s_nop 1
	v_add_f32_dpp v61, v60, v60 quad_perm:[1,0,3,2] row_mask:0xf bank_mask:0xf
	s_nop 1
	v_add_f32_dpp v60, v61, v61 quad_perm:[2,3,0,1] row_mask:0xf bank_mask:0xf
	s_nop 1
	v_add_f32_dpp v61, v60, v60 row_half_mirror row_mask:0xf bank_mask:0xf
	s_nop 1
	v_add_f32_dpp v60, v61, v61 row_mirror row_mask:0xf bank_mask:0xf
	v_mov_b32_e32 v61, v60
	s_nop 1
	v_add_f32_dpp v61, v60, v60 row_bcast:15 row_mask:0xa bank_mask:0xf
	s_nop 1
	v_mov_b32_e32 v60, v61
	s_nop 1
	v_add_f32_dpp v60, v61, v61 row_bcast:31 row_mask:0xc bank_mask:0xf
	s_nop 1
	v_readlane_b32 s16, v60, 63
	s_nop 1
	v_mov_b32_e32 v148, s16
	v_fmamk_f32 v148, v148, 0x3a800000, v66
	v_rsq_f32_e32 v148, v148
	s_nop 0
	s_waitcnt vmcnt(16)
	v_pk_mul_f32 v[16:17], v[16:17], v[148:149] op_sel_hi:[1,0]
	v_pk_mul_f32 v[18:19], v[18:19], v[148:149] op_sel_hi:[1,0]
	v_pk_add_f32 v[116:117], v[116:117], 1.0 op_sel_hi:[1,0]
	v_pk_add_f32 v[118:119], v[118:119], 1.0 op_sel_hi:[1,0]
	v_pk_mul_f32 v[16:17], v[0:1], v[16:17]
	v_pk_mul_f32 v[18:19], v[2:3], v[18:19]
	v_pk_fma_f32 v[16:17], v[16:17], v[116:117], v[132:133]
	v_pk_fma_f32 v[18:19], v[18:19], v[118:119], v[134:135]
	v_cvt_pk_bf16_f32 v16, v16, v17
	v_cvt_pk_bf16_f32 v17, v18, v19
	global_store_dwordx2 v48, v[16:17], s[14:15]
	v_pk_mul_f32 v[20:21], v[20:21], v[148:149] op_sel_hi:[1,0]
	v_pk_mul_f32 v[22:23], v[22:23], v[148:149] op_sel_hi:[1,0]
	v_pk_add_f32 v[120:121], v[120:121], 1.0 op_sel_hi:[1,0]
	v_pk_add_f32 v[122:123], v[122:123], 1.0 op_sel_hi:[1,0]
	v_pk_mul_f32 v[20:21], v[4:5], v[20:21]
	v_pk_mul_f32 v[22:23], v[6:7], v[22:23]
	v_pk_fma_f32 v[20:21], v[20:21], v[120:121], v[136:137]
	v_pk_fma_f32 v[22:23], v[22:23], v[122:123], v[138:139]
	v_cvt_pk_bf16_f32 v20, v20, v21
	v_cvt_pk_bf16_f32 v21, v22, v23
	global_store_dwordx2 v48, v[20:21], s[14:15] offset:512
	v_pk_mul_f32 v[24:25], v[24:25], v[148:149] op_sel_hi:[1,0]
	v_pk_mul_f32 v[26:27], v[26:27], v[148:149] op_sel_hi:[1,0]
	v_pk_add_f32 v[124:125], v[124:125], 1.0 op_sel_hi:[1,0]
	v_pk_add_f32 v[126:127], v[126:127], 1.0 op_sel_hi:[1,0]
	v_pk_mul_f32 v[24:25], v[8:9], v[24:25]
	v_pk_mul_f32 v[26:27], v[10:11], v[26:27]
	v_pk_fma_f32 v[24:25], v[24:25], v[124:125], v[140:141]
	v_pk_fma_f32 v[26:27], v[26:27], v[126:127], v[142:143]
	v_cvt_pk_bf16_f32 v24, v24, v25
	v_cvt_pk_bf16_f32 v25, v26, v27
	global_store_dwordx2 v48, v[24:25], s[14:15] offset:1024
	v_pk_mul_f32 v[28:29], v[28:29], v[148:149] op_sel_hi:[1,0]
	v_pk_mul_f32 v[30:31], v[30:31], v[148:149] op_sel_hi:[1,0]
	v_pk_add_f32 v[128:129], v[128:129], 1.0 op_sel_hi:[1,0]
	v_pk_add_f32 v[130:131], v[130:131], 1.0 op_sel_hi:[1,0]
	v_pk_mul_f32 v[28:29], v[12:13], v[28:29]
	v_pk_mul_f32 v[30:31], v[14:15], v[30:31]
	v_pk_fma_f32 v[28:29], v[28:29], v[128:129], v[144:145]
	v_pk_fma_f32 v[30:31], v[30:31], v[130:131], v[146:147]
	v_cvt_pk_bf16_f32 v28, v28, v29
	v_cvt_pk_bf16_f32 v29, v30, v31
	global_store_dwordx2 v48, v[28:29], s[14:15] offset:1536
	s_add_u32 s14, s14, 0x400000
	s_addc_u32 s15, s15, 0
	global_load_dwordx4 v[16:19], v56, s[0:1] nt
	global_load_dwordx4 v[20:23], v56, s[0:1] offset:1024 nt
	global_load_dwordx4 v[24:27], v56, s[0:1] offset:2048 nt
	global_load_dwordx4 v[28:31], v56, s[0:1] offset:3072 nt
	s_add_u32 s0, s0, 0x800000
	s_addc_u32 s1, s1, 0
	global_load_dwordx4 v[132:135], v56, s[10:11]
	global_load_dwordx4 v[136:139], v56, s[10:11] offset:1024
	global_load_dwordx4 v[140:143], v56, s[10:11] offset:2048
	global_load_dwordx4 v[144:147], v56, s[10:11] offset:3072
	global_load_dwordx4 v[116:119], v56, s[12:13]
	global_load_dwordx4 v[120:123], v56, s[12:13] offset:1024
	global_load_dwordx4 v[124:127], v56, s[12:13] offset:2048
	global_load_dwordx4 v[128:131], v56, s[12:13] offset:3072
	s_add_u32 s10, s10, 0x6000
	s_addc_u32 s11, s11, 0
	s_add_u32 s12, s12, 0x6000
	s_addc_u32 s13, s13, 0
	s_waitcnt vmcnt(40)
	v_pk_mul_f32 v[58:59], v[32:33], v[32:33]
	v_pk_fma_f32 v[58:59], v[34:35], v[34:35], v[58:59]
	v_pk_fma_f32 v[58:59], v[36:37], v[36:37], v[58:59]
	v_pk_fma_f32 v[58:59], v[38:39], v[38:39], v[58:59]
	v_pk_fma_f32 v[58:59], v[40:41], v[40:41], v[58:59]
	v_pk_fma_f32 v[58:59], v[42:43], v[42:43], v[58:59]
	v_pk_fma_f32 v[58:59], v[44:45], v[44:45], v[58:59]
	v_pk_fma_f32 v[58:59], v[46:47], v[46:47], v[58:59]
	v_add_f32_e32 v60, v58, v59
	s_nop 1
	v_add_f32_dpp v61, v60, v60 quad_perm:[1,0,3,2] row_mask:0xf bank_mask:0xf
	s_nop 1
	v_add_f32_dpp v60, v61, v61 quad_perm:[2,3,0,1] row_mask:0xf bank_mask:0xf
	s_nop 1
	v_add_f32_dpp v61, v60, v60 row_half_mirror row_mask:0xf bank_mask:0xf
	s_nop 1
	v_add_f32_dpp v60, v61, v61 row_mirror row_mask:0xf bank_mask:0xf
	v_mov_b32_e32 v61, v60
	s_nop 1
	v_add_f32_dpp v61, v60, v60 row_bcast:15 row_mask:0xa bank_mask:0xf
	s_nop 1
	v_mov_b32_e32 v60, v61
	s_nop 1
	v_add_f32_dpp v60, v61, v61 row_bcast:31 row_mask:0xc bank_mask:0xf
	s_nop 1
	v_readlane_b32 s16, v60, 63
	s_nop 1
	v_mov_b32_e32 v148, s16
	v_fmamk_f32 v148, v148, 0x3a800000, v66
	v_rsq_f32_e32 v148, v148
	s_nop 0
	s_waitcnt vmcnt(16)
	v_pk_mul_f32 v[32:33], v[32:33], v[148:149] op_sel_hi:[1,0]
	v_pk_mul_f32 v[34:35], v[34:35], v[148:149] op_sel_hi:[1,0]
	v_pk_add_f32 v[84:85], v[84:85], 1.0 op_sel_hi:[1,0]
	v_pk_add_f32 v[86:87], v[86:87], 1.0 op_sel_hi:[1,0]
	v_pk_mul_f32 v[32:33], v[0:1], v[32:33]
	v_pk_mul_f32 v[34:35], v[2:3], v[34:35]
	v_pk_fma_f32 v[32:33], v[32:33], v[84:85], v[100:101]
	v_pk_fma_f32 v[34:35], v[34:35], v[86:87], v[102:103]
	v_cvt_pk_bf16_f32 v32, v32, v33
	v_cvt_pk_bf16_f32 v33, v34, v35
	global_store_dwordx2 v48, v[32:33], s[14:15]
	v_pk_mul_f32 v[36:37], v[36:37], v[148:149] op_sel_hi:[1,0]
	v_pk_mul_f32 v[38:39], v[38:39], v[148:149] op_sel_hi:[1,0]
	v_pk_add_f32 v[88:89], v[88:89], 1.0 op_sel_hi:[1,0]
	v_pk_add_f32 v[90:91], v[90:91], 1.0 op_sel_hi:[1,0]
	v_pk_mul_f32 v[36:37], v[4:5], v[36:37]
	v_pk_mul_f32 v[38:39], v[6:7], v[38:39]
	v_pk_fma_f32 v[36:37], v[36:37], v[88:89], v[104:105]
	v_pk_fma_f32 v[38:39], v[38:39], v[90:91], v[106:107]
	v_cvt_pk_bf16_f32 v36, v36, v37
	v_cvt_pk_bf16_f32 v37, v38, v39
	global_store_dwordx2 v48, v[36:37], s[14:15] offset:512
	v_pk_mul_f32 v[40:41], v[40:41], v[148:149] op_sel_hi:[1,0]
	v_pk_mul_f32 v[42:43], v[42:43], v[148:149] op_sel_hi:[1,0]
	v_pk_add_f32 v[92:93], v[92:93], 1.0 op_sel_hi:[1,0]
	v_pk_add_f32 v[94:95], v[94:95], 1.0 op_sel_hi:[1,0]
	v_pk_mul_f32 v[40:41], v[8:9], v[40:41]
	v_pk_mul_f32 v[42:43], v[10:11], v[42:43]
	v_pk_fma_f32 v[40:41], v[40:41], v[92:93], v[108:109]
	v_pk_fma_f32 v[42:43], v[42:43], v[94:95], v[110:111]
	v_cvt_pk_bf16_f32 v40, v40, v41
	v_cvt_pk_bf16_f32 v41, v42, v43
	global_store_dwordx2 v48, v[40:41], s[14:15] offset:1024
	v_pk_mul_f32 v[44:45], v[44:45], v[148:149] op_sel_hi:[1,0]
	v_pk_mul_f32 v[46:47], v[46:47], v[148:149] op_sel_hi:[1,0]
	v_pk_add_f32 v[96:97], v[96:97], 1.0 op_sel_hi:[1,0]
	v_pk_add_f32 v[98:99], v[98:99], 1.0 op_sel_hi:[1,0]
	v_pk_mul_f32 v[44:45], v[12:13], v[44:45]
	v_pk_mul_f32 v[46:47], v[14:15], v[46:47]
	v_pk_fma_f32 v[44:45], v[44:45], v[96:97], v[112:113]
	v_pk_fma_f32 v[46:47], v[46:47], v[98:99], v[114:115]
	v_cvt_pk_bf16_f32 v44, v44, v45
	v_cvt_pk_bf16_f32 v45, v46, v47
	global_store_dwordx2 v48, v[44:45], s[14:15] offset:1536
	s_add_u32 s14, s14, 0x400000
	s_addc_u32 s15, s15, 0
	global_load_dwordx4 v[32:35], v56, s[0:1] nt
	global_load_dwordx4 v[36:39], v56, s[0:1] offset:1024 nt
	global_load_dwordx4 v[40:43], v56, s[0:1] offset:2048 nt
	global_load_dwordx4 v[44:47], v56, s[0:1] offset:3072 nt
	s_add_u32 s0, s0, 0x800000
	s_addc_u32 s1, s1, 0
	global_load_dwordx4 v[100:103], v56, s[10:11]
	global_load_dwordx4 v[104:107], v56, s[10:11] offset:1024
	global_load_dwordx4 v[108:111], v56, s[10:11] offset:2048
	global_load_dwordx4 v[112:115], v56, s[10:11] offset:3072
	global_load_dwordx4 v[84:87], v56, s[12:13]
	global_load_dwordx4 v[88:91], v56, s[12:13] offset:1024
	global_load_dwordx4 v[92:95], v56, s[12:13] offset:2048
	global_load_dwordx4 v[96:99], v56, s[12:13] offset:3072
	s_add_u32 s10, s10, 0x6000
	s_addc_u32 s11, s11, 0
	s_add_u32 s12, s12, 0x6000
	s_addc_u32 s13, s13, 0
	s_waitcnt vmcnt(40)
	v_pk_mul_f32 v[58:59], v[68:69], v[68:69]
	v_pk_fma_f32 v[58:59], v[70:71], v[70:71], v[58:59]
	v_pk_fma_f32 v[58:59], v[72:73], v[72:73], v[58:59]
	v_pk_fma_f32 v[58:59], v[74:75], v[74:75], v[58:59]
	v_pk_fma_f32 v[58:59], v[76:77], v[76:77], v[58:59]
	v_pk_fma_f32 v[58:59], v[78:79], v[78:79], v[58:59]
	v_pk_fma_f32 v[58:59], v[80:81], v[80:81], v[58:59]
	v_pk_fma_f32 v[58:59], v[82:83], v[82:83], v[58:59]
	v_add_f32_e32 v60, v58, v59
	s_nop 1
	v_add_f32_dpp v61, v60, v60 quad_perm:[1,0,3,2] row_mask:0xf bank_mask:0xf
	s_nop 1
	v_add_f32_dpp v60, v61, v61 quad_perm:[2,3,0,1] row_mask:0xf bank_mask:0xf
	s_nop 1
	v_add_f32_dpp v61, v60, v60 row_half_mirror row_mask:0xf bank_mask:0xf
	s_nop 1
	v_add_f32_dpp v60, v61, v61 row_mirror row_mask:0xf bank_mask:0xf
	v_mov_b32_e32 v61, v60
	s_nop 1
	v_add_f32_dpp v61, v60, v60 row_bcast:15 row_mask:0xa bank_mask:0xf
	s_nop 1
	v_mov_b32_e32 v60, v61
	s_nop 1
	v_add_f32_dpp v60, v61, v61 row_bcast:31 row_mask:0xc bank_mask:0xf
	s_nop 1
	v_readlane_b32 s16, v60, 63
	s_nop 1
	v_mov_b32_e32 v148, s16
	v_fmamk_f32 v148, v148, 0x3a800000, v66
	v_rsq_f32_e32 v148, v148
	s_nop 0
	s_waitcnt vmcnt(16)
	v_pk_mul_f32 v[68:69], v[68:69], v[148:149] op_sel_hi:[1,0]
	v_pk_mul_f32 v[70:71], v[70:71], v[148:149] op_sel_hi:[1,0]
	v_pk_add_f32 v[116:117], v[116:117], 1.0 op_sel_hi:[1,0]
	v_pk_add_f32 v[118:119], v[118:119], 1.0 op_sel_hi:[1,0]
	v_pk_mul_f32 v[68:69], v[0:1], v[68:69]
	v_pk_mul_f32 v[70:71], v[2:3], v[70:71]
	v_pk_fma_f32 v[68:69], v[68:69], v[116:117], v[132:133]
	v_pk_fma_f32 v[70:71], v[70:71], v[118:119], v[134:135]
	v_cvt_pk_bf16_f32 v68, v68, v69
	v_cvt_pk_bf16_f32 v69, v70, v71
	global_store_dwordx2 v48, v[68:69], s[14:15]
	v_pk_mul_f32 v[72:73], v[72:73], v[148:149] op_sel_hi:[1,0]
	v_pk_mul_f32 v[74:75], v[74:75], v[148:149] op_sel_hi:[1,0]
	v_pk_add_f32 v[120:121], v[120:121], 1.0 op_sel_hi:[1,0]
	v_pk_add_f32 v[122:123], v[122:123], 1.0 op_sel_hi:[1,0]
	v_pk_mul_f32 v[72:73], v[4:5], v[72:73]
	v_pk_mul_f32 v[74:75], v[6:7], v[74:75]
	v_pk_fma_f32 v[72:73], v[72:73], v[120:121], v[136:137]
	v_pk_fma_f32 v[74:75], v[74:75], v[122:123], v[138:139]
	v_cvt_pk_bf16_f32 v72, v72, v73
	v_cvt_pk_bf16_f32 v73, v74, v75
	global_store_dwordx2 v48, v[72:73], s[14:15] offset:512
	v_pk_mul_f32 v[76:77], v[76:77], v[148:149] op_sel_hi:[1,0]
	v_pk_mul_f32 v[78:79], v[78:79], v[148:149] op_sel_hi:[1,0]
	v_pk_add_f32 v[124:125], v[124:125], 1.0 op_sel_hi:[1,0]
	v_pk_add_f32 v[126:127], v[126:127], 1.0 op_sel_hi:[1,0]
	v_pk_mul_f32 v[76:77], v[8:9], v[76:77]
	v_pk_mul_f32 v[78:79], v[10:11], v[78:79]
	v_pk_fma_f32 v[76:77], v[76:77], v[124:125], v[140:141]
	v_pk_fma_f32 v[78:79], v[78:79], v[126:127], v[142:143]
	v_cvt_pk_bf16_f32 v76, v76, v77
	v_cvt_pk_bf16_f32 v77, v78, v79
	global_store_dwordx2 v48, v[76:77], s[14:15] offset:1024
	v_pk_mul_f32 v[80:81], v[80:81], v[148:149] op_sel_hi:[1,0]
	v_pk_mul_f32 v[82:83], v[82:83], v[148:149] op_sel_hi:[1,0]
	v_pk_add_f32 v[128:129], v[128:129], 1.0 op_sel_hi:[1,0]
	v_pk_add_f32 v[130:131], v[130:131], 1.0 op_sel_hi:[1,0]
	v_pk_mul_f32 v[80:81], v[12:13], v[80:81]
	v_pk_mul_f32 v[82:83], v[14:15], v[82:83]
	v_pk_fma_f32 v[80:81], v[80:81], v[128:129], v[144:145]
	v_pk_fma_f32 v[82:83], v[82:83], v[130:131], v[146:147]
	v_cvt_pk_bf16_f32 v80, v80, v81
	v_cvt_pk_bf16_f32 v81, v82, v83
	global_store_dwordx2 v48, v[80:81], s[14:15] offset:1536
	s_add_u32 s14, s14, 0x400000
	s_addc_u32 s15, s15, 0
	global_load_dwordx4 v[68:71], v56, s[0:1] nt
	global_load_dwordx4 v[72:75], v56, s[0:1] offset:1024 nt
	global_load_dwordx4 v[76:79], v56, s[0:1] offset:2048 nt
	global_load_dwordx4 v[80:83], v56, s[0:1] offset:3072 nt
	s_add_u32 s0, s0, 0x800000
	s_addc_u32 s1, s1, 0
	global_load_dwordx4 v[132:135], v56, s[10:11]
	global_load_dwordx4 v[136:139], v56, s[10:11] offset:1024
	global_load_dwordx4 v[140:143], v56, s[10:11] offset:2048
	global_load_dwordx4 v[144:147], v56, s[10:11] offset:3072
	global_load_dwordx4 v[116:119], v56, s[12:13]
	global_load_dwordx4 v[120:123], v56, s[12:13] offset:1024
	global_load_dwordx4 v[124:127], v56, s[12:13] offset:2048
	global_load_dwordx4 v[128:131], v56, s[12:13] offset:3072
	s_add_u32 s10, s10, 0x6000
	s_addc_u32 s11, s11, 0
	s_add_u32 s12, s12, 0x6000
	s_addc_u32 s13, s13, 0
	s_waitcnt vmcnt(40)
	v_pk_mul_f32 v[58:59], v[16:17], v[16:17]
	v_pk_fma_f32 v[58:59], v[18:19], v[18:19], v[58:59]
	v_pk_fma_f32 v[58:59], v[20:21], v[20:21], v[58:59]
	v_pk_fma_f32 v[58:59], v[22:23], v[22:23], v[58:59]
	v_pk_fma_f32 v[58:59], v[24:25], v[24:25], v[58:59]
	v_pk_fma_f32 v[58:59], v[26:27], v[26:27], v[58:59]
	v_pk_fma_f32 v[58:59], v[28:29], v[28:29], v[58:59]
	v_pk_fma_f32 v[58:59], v[30:31], v[30:31], v[58:59]
	v_add_f32_e32 v60, v58, v59
	s_nop 1
	v_add_f32_dpp v61, v60, v60 quad_perm:[1,0,3,2] row_mask:0xf bank_mask:0xf
	s_nop 1
	v_add_f32_dpp v60, v61, v61 quad_perm:[2,3,0,1] row_mask:0xf bank_mask:0xf
	s_nop 1
	v_add_f32_dpp v61, v60, v60 row_half_mirror row_mask:0xf bank_mask:0xf
	s_nop 1
	v_add_f32_dpp v60, v61, v61 row_mirror row_mask:0xf bank_mask:0xf
	v_mov_b32_e32 v61, v60
	s_nop 1
	v_add_f32_dpp v61, v60, v60 row_bcast:15 row_mask:0xa bank_mask:0xf
	s_nop 1
	v_mov_b32_e32 v60, v61
	s_nop 1
	v_add_f32_dpp v60, v61, v61 row_bcast:31 row_mask:0xc bank_mask:0xf
	s_nop 1
	v_readlane_b32 s16, v60, 63
	s_nop 1
	v_mov_b32_e32 v148, s16
	v_fmamk_f32 v148, v148, 0x3a800000, v66
	v_rsq_f32_e32 v148, v148
	s_nop 0
	s_waitcnt vmcnt(16)
	v_pk_mul_f32 v[16:17], v[16:17], v[148:149] op_sel_hi:[1,0]
	v_pk_mul_f32 v[18:19], v[18:19], v[148:149] op_sel_hi:[1,0]
	v_pk_add_f32 v[84:85], v[84:85], 1.0 op_sel_hi:[1,0]
	v_pk_add_f32 v[86:87], v[86:87], 1.0 op_sel_hi:[1,0]
	v_pk_mul_f32 v[16:17], v[0:1], v[16:17]
	v_pk_mul_f32 v[18:19], v[2:3], v[18:19]
	v_pk_fma_f32 v[16:17], v[16:17], v[84:85], v[100:101]
	v_pk_fma_f32 v[18:19], v[18:19], v[86:87], v[102:103]
	v_cvt_pk_bf16_f32 v16, v16, v17
	v_cvt_pk_bf16_f32 v17, v18, v19
	global_store_dwordx2 v48, v[16:17], s[14:15]
	v_pk_mul_f32 v[20:21], v[20:21], v[148:149] op_sel_hi:[1,0]
	v_pk_mul_f32 v[22:23], v[22:23], v[148:149] op_sel_hi:[1,0]
	v_pk_add_f32 v[88:89], v[88:89], 1.0 op_sel_hi:[1,0]
	v_pk_add_f32 v[90:91], v[90:91], 1.0 op_sel_hi:[1,0]
	v_pk_mul_f32 v[20:21], v[4:5], v[20:21]
	v_pk_mul_f32 v[22:23], v[6:7], v[22:23]
	v_pk_fma_f32 v[20:21], v[20:21], v[88:89], v[104:105]
	v_pk_fma_f32 v[22:23], v[22:23], v[90:91], v[106:107]
	v_cvt_pk_bf16_f32 v20, v20, v21
	v_cvt_pk_bf16_f32 v21, v22, v23
	global_store_dwordx2 v48, v[20:21], s[14:15] offset:512
	v_pk_mul_f32 v[24:25], v[24:25], v[148:149] op_sel_hi:[1,0]
	v_pk_mul_f32 v[26:27], v[26:27], v[148:149] op_sel_hi:[1,0]
	v_pk_add_f32 v[92:93], v[92:93], 1.0 op_sel_hi:[1,0]
	v_pk_add_f32 v[94:95], v[94:95], 1.0 op_sel_hi:[1,0]
	v_pk_mul_f32 v[24:25], v[8:9], v[24:25]
	v_pk_mul_f32 v[26:27], v[10:11], v[26:27]
	v_pk_fma_f32 v[24:25], v[24:25], v[92:93], v[108:109]
	v_pk_fma_f32 v[26:27], v[26:27], v[94:95], v[110:111]
	v_cvt_pk_bf16_f32 v24, v24, v25
	v_cvt_pk_bf16_f32 v25, v26, v27
	global_store_dwordx2 v48, v[24:25], s[14:15] offset:1024
	v_pk_mul_f32 v[28:29], v[28:29], v[148:149] op_sel_hi:[1,0]
	v_pk_mul_f32 v[30:31], v[30:31], v[148:149] op_sel_hi:[1,0]
	v_pk_add_f32 v[96:97], v[96:97], 1.0 op_sel_hi:[1,0]
	v_pk_add_f32 v[98:99], v[98:99], 1.0 op_sel_hi:[1,0]
	v_pk_mul_f32 v[28:29], v[12:13], v[28:29]
	v_pk_mul_f32 v[30:31], v[14:15], v[30:31]
	v_pk_fma_f32 v[28:29], v[28:29], v[96:97], v[112:113]
	v_pk_fma_f32 v[30:31], v[30:31], v[98:99], v[114:115]
	v_cvt_pk_bf16_f32 v28, v28, v29
	v_cvt_pk_bf16_f32 v29, v30, v31
	global_store_dwordx2 v48, v[28:29], s[14:15] offset:1536
	s_add_u32 s14, s14, 0x400000
	s_addc_u32 s15, s15, 0
	global_load_dwordx4 v[16:19], v56, s[0:1] nt
	global_load_dwordx4 v[20:23], v56, s[0:1] offset:1024 nt
	global_load_dwordx4 v[24:27], v56, s[0:1] offset:2048 nt
	global_load_dwordx4 v[28:31], v56, s[0:1] offset:3072 nt
	s_add_u32 s0, s0, 0x800000
	s_addc_u32 s1, s1, 0
	global_load_dwordx4 v[100:103], v56, s[10:11]
	global_load_dwordx4 v[104:107], v56, s[10:11] offset:1024
	global_load_dwordx4 v[108:111], v56, s[10:11] offset:2048
	global_load_dwordx4 v[112:115], v56, s[10:11] offset:3072
	global_load_dwordx4 v[84:87], v56, s[12:13]
	global_load_dwordx4 v[88:91], v56, s[12:13] offset:1024
	global_load_dwordx4 v[92:95], v56, s[12:13] offset:2048
	global_load_dwordx4 v[96:99], v56, s[12:13] offset:3072
	s_add_u32 s10, s10, 0x6000
	s_addc_u32 s11, s11, 0
	s_add_u32 s12, s12, 0x6000
	s_addc_u32 s13, s13, 0
	s_waitcnt vmcnt(40)
	v_pk_mul_f32 v[58:59], v[32:33], v[32:33]
	v_pk_fma_f32 v[58:59], v[34:35], v[34:35], v[58:59]
	v_pk_fma_f32 v[58:59], v[36:37], v[36:37], v[58:59]
	v_pk_fma_f32 v[58:59], v[38:39], v[38:39], v[58:59]
	v_pk_fma_f32 v[58:59], v[40:41], v[40:41], v[58:59]
	v_pk_fma_f32 v[58:59], v[42:43], v[42:43], v[58:59]
	v_pk_fma_f32 v[58:59], v[44:45], v[44:45], v[58:59]
	v_pk_fma_f32 v[58:59], v[46:47], v[46:47], v[58:59]
	v_add_f32_e32 v60, v58, v59
	s_nop 1
	v_add_f32_dpp v61, v60, v60 quad_perm:[1,0,3,2] row_mask:0xf bank_mask:0xf
	s_nop 1
	v_add_f32_dpp v60, v61, v61 quad_perm:[2,3,0,1] row_mask:0xf bank_mask:0xf
	s_nop 1
	v_add_f32_dpp v61, v60, v60 row_half_mirror row_mask:0xf bank_mask:0xf
	s_nop 1
	v_add_f32_dpp v60, v61, v61 row_mirror row_mask:0xf bank_mask:0xf
	v_mov_b32_e32 v61, v60
	s_nop 1
	v_add_f32_dpp v61, v60, v60 row_bcast:15 row_mask:0xa bank_mask:0xf
	s_nop 1
	v_mov_b32_e32 v60, v61
	s_nop 1
	v_add_f32_dpp v60, v61, v61 row_bcast:31 row_mask:0xc bank_mask:0xf
	s_nop 1
	v_readlane_b32 s16, v60, 63
	s_nop 1
	v_mov_b32_e32 v148, s16
	v_fmamk_f32 v148, v148, 0x3a800000, v66
	v_rsq_f32_e32 v148, v148
	s_nop 0
	s_waitcnt vmcnt(16)
	v_pk_mul_f32 v[32:33], v[32:33], v[148:149] op_sel_hi:[1,0]
	v_pk_mul_f32 v[34:35], v[34:35], v[148:149] op_sel_hi:[1,0]
	v_pk_add_f32 v[116:117], v[116:117], 1.0 op_sel_hi:[1,0]
	v_pk_add_f32 v[118:119], v[118:119], 1.0 op_sel_hi:[1,0]
	v_pk_mul_f32 v[32:33], v[0:1], v[32:33]
	v_pk_mul_f32 v[34:35], v[2:3], v[34:35]
	v_pk_fma_f32 v[32:33], v[32:33], v[116:117], v[132:133]
	v_pk_fma_f32 v[34:35], v[34:35], v[118:119], v[134:135]
	v_cvt_pk_bf16_f32 v32, v32, v33
	v_cvt_pk_bf16_f32 v33, v34, v35
	global_store_dwordx2 v48, v[32:33], s[14:15]
	v_pk_mul_f32 v[36:37], v[36:37], v[148:149] op_sel_hi:[1,0]
	v_pk_mul_f32 v[38:39], v[38:39], v[148:149] op_sel_hi:[1,0]
	v_pk_add_f32 v[120:121], v[120:121], 1.0 op_sel_hi:[1,0]
	v_pk_add_f32 v[122:123], v[122:123], 1.0 op_sel_hi:[1,0]
	v_pk_mul_f32 v[36:37], v[4:5], v[36:37]
	v_pk_mul_f32 v[38:39], v[6:7], v[38:39]
	v_pk_fma_f32 v[36:37], v[36:37], v[120:121], v[136:137]
	v_pk_fma_f32 v[38:39], v[38:39], v[122:123], v[138:139]
	v_cvt_pk_bf16_f32 v36, v36, v37
	v_cvt_pk_bf16_f32 v37, v38, v39
	global_store_dwordx2 v48, v[36:37], s[14:15] offset:512
	v_pk_mul_f32 v[40:41], v[40:41], v[148:149] op_sel_hi:[1,0]
	v_pk_mul_f32 v[42:43], v[42:43], v[148:149] op_sel_hi:[1,0]
	v_pk_add_f32 v[124:125], v[124:125], 1.0 op_sel_hi:[1,0]
	v_pk_add_f32 v[126:127], v[126:127], 1.0 op_sel_hi:[1,0]
	v_pk_mul_f32 v[40:41], v[8:9], v[40:41]
	v_pk_mul_f32 v[42:43], v[10:11], v[42:43]
	v_pk_fma_f32 v[40:41], v[40:41], v[124:125], v[140:141]
	v_pk_fma_f32 v[42:43], v[42:43], v[126:127], v[142:143]
	v_cvt_pk_bf16_f32 v40, v40, v41
	v_cvt_pk_bf16_f32 v41, v42, v43
	global_store_dwordx2 v48, v[40:41], s[14:15] offset:1024
	v_pk_mul_f32 v[44:45], v[44:45], v[148:149] op_sel_hi:[1,0]
	v_pk_mul_f32 v[46:47], v[46:47], v[148:149] op_sel_hi:[1,0]
	v_pk_add_f32 v[128:129], v[128:129], 1.0 op_sel_hi:[1,0]
	v_pk_add_f32 v[130:131], v[130:131], 1.0 op_sel_hi:[1,0]
	v_pk_mul_f32 v[44:45], v[12:13], v[44:45]
	v_pk_mul_f32 v[46:47], v[14:15], v[46:47]
	v_pk_fma_f32 v[44:45], v[44:45], v[128:129], v[144:145]
	v_pk_fma_f32 v[46:47], v[46:47], v[130:131], v[146:147]
	v_cvt_pk_bf16_f32 v44, v44, v45
	v_cvt_pk_bf16_f32 v45, v46, v47
	global_store_dwordx2 v48, v[44:45], s[14:15] offset:1536
	s_add_u32 s14, s14, 0x400000
	s_addc_u32 s15, s15, 0
	global_load_dwordx4 v[32:35], v56, s[0:1] nt
	global_load_dwordx4 v[36:39], v56, s[0:1] offset:1024 nt
	global_load_dwordx4 v[40:43], v56, s[0:1] offset:2048 nt
	global_load_dwordx4 v[44:47], v56, s[0:1] offset:3072 nt
	s_add_u32 s0, s0, 0x800000
	s_addc_u32 s1, s1, 0
	global_load_dwordx4 v[132:135], v56, s[10:11]
	global_load_dwordx4 v[136:139], v56, s[10:11] offset:1024
	global_load_dwordx4 v[140:143], v56, s[10:11] offset:2048
	global_load_dwordx4 v[144:147], v56, s[10:11] offset:3072
	global_load_dwordx4 v[116:119], v56, s[12:13]
	global_load_dwordx4 v[120:123], v56, s[12:13] offset:1024
	global_load_dwordx4 v[124:127], v56, s[12:13] offset:2048
	global_load_dwordx4 v[128:131], v56, s[12:13] offset:3072
	s_add_u32 s10, s10, 0x6000
	s_addc_u32 s11, s11, 0
	s_add_u32 s12, s12, 0x6000
	s_addc_u32 s13, s13, 0
	s_waitcnt vmcnt(40)
	v_pk_mul_f32 v[58:59], v[68:69], v[68:69]
	v_pk_fma_f32 v[58:59], v[70:71], v[70:71], v[58:59]
	v_pk_fma_f32 v[58:59], v[72:73], v[72:73], v[58:59]
	v_pk_fma_f32 v[58:59], v[74:75], v[74:75], v[58:59]
	v_pk_fma_f32 v[58:59], v[76:77], v[76:77], v[58:59]
	v_pk_fma_f32 v[58:59], v[78:79], v[78:79], v[58:59]
	v_pk_fma_f32 v[58:59], v[80:81], v[80:81], v[58:59]
	v_pk_fma_f32 v[58:59], v[82:83], v[82:83], v[58:59]
	v_add_f32_e32 v60, v58, v59
	s_nop 1
	v_add_f32_dpp v61, v60, v60 quad_perm:[1,0,3,2] row_mask:0xf bank_mask:0xf
	s_nop 1
	v_add_f32_dpp v60, v61, v61 quad_perm:[2,3,0,1] row_mask:0xf bank_mask:0xf
	s_nop 1
	v_add_f32_dpp v61, v60, v60 row_half_mirror row_mask:0xf bank_mask:0xf
	s_nop 1
	v_add_f32_dpp v60, v61, v61 row_mirror row_mask:0xf bank_mask:0xf
	v_mov_b32_e32 v61, v60
	s_nop 1
	v_add_f32_dpp v61, v60, v60 row_bcast:15 row_mask:0xa bank_mask:0xf
	s_nop 1
	v_mov_b32_e32 v60, v61
	s_nop 1
	v_add_f32_dpp v60, v61, v61 row_bcast:31 row_mask:0xc bank_mask:0xf
	s_nop 1
	v_readlane_b32 s16, v60, 63
	s_nop 1
	v_mov_b32_e32 v148, s16
	v_fmamk_f32 v148, v148, 0x3a800000, v66
	v_rsq_f32_e32 v148, v148
	s_nop 0
	s_waitcnt vmcnt(16)
	v_pk_mul_f32 v[68:69], v[68:69], v[148:149] op_sel_hi:[1,0]
	v_pk_mul_f32 v[70:71], v[70:71], v[148:149] op_sel_hi:[1,0]
	v_pk_add_f32 v[84:85], v[84:85], 1.0 op_sel_hi:[1,0]
	v_pk_add_f32 v[86:87], v[86:87], 1.0 op_sel_hi:[1,0]
	v_pk_mul_f32 v[68:69], v[0:1], v[68:69]
	v_pk_mul_f32 v[70:71], v[2:3], v[70:71]
	v_pk_fma_f32 v[68:69], v[68:69], v[84:85], v[100:101]
	v_pk_fma_f32 v[70:71], v[70:71], v[86:87], v[102:103]
	v_cvt_pk_bf16_f32 v68, v68, v69
	v_cvt_pk_bf16_f32 v69, v70, v71
	global_store_dwordx2 v48, v[68:69], s[14:15]
	v_pk_mul_f32 v[72:73], v[72:73], v[148:149] op_sel_hi:[1,0]
	v_pk_mul_f32 v[74:75], v[74:75], v[148:149] op_sel_hi:[1,0]
	v_pk_add_f32 v[88:89], v[88:89], 1.0 op_sel_hi:[1,0]
	v_pk_add_f32 v[90:91], v[90:91], 1.0 op_sel_hi:[1,0]
	v_pk_mul_f32 v[72:73], v[4:5], v[72:73]
	v_pk_mul_f32 v[74:75], v[6:7], v[74:75]
	v_pk_fma_f32 v[72:73], v[72:73], v[88:89], v[104:105]
	v_pk_fma_f32 v[74:75], v[74:75], v[90:91], v[106:107]
	v_cvt_pk_bf16_f32 v72, v72, v73
	v_cvt_pk_bf16_f32 v73, v74, v75
	global_store_dwordx2 v48, v[72:73], s[14:15] offset:512
	v_pk_mul_f32 v[76:77], v[76:77], v[148:149] op_sel_hi:[1,0]
	v_pk_mul_f32 v[78:79], v[78:79], v[148:149] op_sel_hi:[1,0]
	v_pk_add_f32 v[92:93], v[92:93], 1.0 op_sel_hi:[1,0]
	v_pk_add_f32 v[94:95], v[94:95], 1.0 op_sel_hi:[1,0]
	v_pk_mul_f32 v[76:77], v[8:9], v[76:77]
	v_pk_mul_f32 v[78:79], v[10:11], v[78:79]
	v_pk_fma_f32 v[76:77], v[76:77], v[92:93], v[108:109]
	v_pk_fma_f32 v[78:79], v[78:79], v[94:95], v[110:111]
	v_cvt_pk_bf16_f32 v76, v76, v77
	v_cvt_pk_bf16_f32 v77, v78, v79
	global_store_dwordx2 v48, v[76:77], s[14:15] offset:1024
	v_pk_mul_f32 v[80:81], v[80:81], v[148:149] op_sel_hi:[1,0]
	v_pk_mul_f32 v[82:83], v[82:83], v[148:149] op_sel_hi:[1,0]
	v_pk_add_f32 v[96:97], v[96:97], 1.0 op_sel_hi:[1,0]
	v_pk_add_f32 v[98:99], v[98:99], 1.0 op_sel_hi:[1,0]
	v_pk_mul_f32 v[80:81], v[12:13], v[80:81]
	v_pk_mul_f32 v[82:83], v[14:15], v[82:83]
	v_pk_fma_f32 v[80:81], v[80:81], v[96:97], v[112:113]
	v_pk_fma_f32 v[82:83], v[82:83], v[98:99], v[114:115]
	v_cvt_pk_bf16_f32 v80, v80, v81
	v_cvt_pk_bf16_f32 v81, v82, v83
	global_store_dwordx2 v48, v[80:81], s[14:15] offset:1536
	s_add_u32 s14, s14, 0x400000
	s_addc_u32 s15, s15, 0
	global_load_dwordx4 v[68:71], v56, s[0:1] nt
	global_load_dwordx4 v[72:75], v56, s[0:1] offset:1024 nt
	global_load_dwordx4 v[76:79], v56, s[0:1] offset:2048 nt
	global_load_dwordx4 v[80:83], v56, s[0:1] offset:3072 nt
	s_add_u32 s0, s0, 0x800000
	s_addc_u32 s1, s1, 0
	global_load_dwordx4 v[100:103], v56, s[10:11]
	global_load_dwordx4 v[104:107], v56, s[10:11] offset:1024
	global_load_dwordx4 v[108:111], v56, s[10:11] offset:2048
	global_load_dwordx4 v[112:115], v56, s[10:11] offset:3072
	global_load_dwordx4 v[84:87], v56, s[12:13]
	global_load_dwordx4 v[88:91], v56, s[12:13] offset:1024
	global_load_dwordx4 v[92:95], v56, s[12:13] offset:2048
	global_load_dwordx4 v[96:99], v56, s[12:13] offset:3072
	s_add_u32 s10, s10, 0x6000
	s_addc_u32 s11, s11, 0
	s_add_u32 s12, s12, 0x6000
	s_addc_u32 s13, s13, 0
	s_waitcnt vmcnt(40)
	v_pk_mul_f32 v[58:59], v[16:17], v[16:17]
	v_pk_fma_f32 v[58:59], v[18:19], v[18:19], v[58:59]
	v_pk_fma_f32 v[58:59], v[20:21], v[20:21], v[58:59]
	v_pk_fma_f32 v[58:59], v[22:23], v[22:23], v[58:59]
	v_pk_fma_f32 v[58:59], v[24:25], v[24:25], v[58:59]
	v_pk_fma_f32 v[58:59], v[26:27], v[26:27], v[58:59]
	v_pk_fma_f32 v[58:59], v[28:29], v[28:29], v[58:59]
	v_pk_fma_f32 v[58:59], v[30:31], v[30:31], v[58:59]
	v_add_f32_e32 v60, v58, v59
	s_nop 1
	v_add_f32_dpp v61, v60, v60 quad_perm:[1,0,3,2] row_mask:0xf bank_mask:0xf
	s_nop 1
	v_add_f32_dpp v60, v61, v61 quad_perm:[2,3,0,1] row_mask:0xf bank_mask:0xf
	s_nop 1
	v_add_f32_dpp v61, v60, v60 row_half_mirror row_mask:0xf bank_mask:0xf
	s_nop 1
	v_add_f32_dpp v60, v61, v61 row_mirror row_mask:0xf bank_mask:0xf
	v_mov_b32_e32 v61, v60
	s_nop 1
	v_add_f32_dpp v61, v60, v60 row_bcast:15 row_mask:0xa bank_mask:0xf
	s_nop 1
	v_mov_b32_e32 v60, v61
	s_nop 1
	v_add_f32_dpp v60, v61, v61 row_bcast:31 row_mask:0xc bank_mask:0xf
	s_nop 1
	v_readlane_b32 s16, v60, 63
	s_nop 1
	v_mov_b32_e32 v148, s16
	v_fmamk_f32 v148, v148, 0x3a800000, v66
	v_rsq_f32_e32 v148, v148
	s_nop 0
	s_waitcnt vmcnt(16)
	v_pk_mul_f32 v[16:17], v[16:17], v[148:149] op_sel_hi:[1,0]
	v_pk_mul_f32 v[18:19], v[18:19], v[148:149] op_sel_hi:[1,0]
	v_pk_add_f32 v[116:117], v[116:117], 1.0 op_sel_hi:[1,0]
	v_pk_add_f32 v[118:119], v[118:119], 1.0 op_sel_hi:[1,0]
	v_pk_mul_f32 v[16:17], v[0:1], v[16:17]
	v_pk_mul_f32 v[18:19], v[2:3], v[18:19]
	v_pk_fma_f32 v[16:17], v[16:17], v[116:117], v[132:133]
	v_pk_fma_f32 v[18:19], v[18:19], v[118:119], v[134:135]
	v_cvt_pk_bf16_f32 v16, v16, v17
	v_cvt_pk_bf16_f32 v17, v18, v19
	global_store_dwordx2 v48, v[16:17], s[14:15]
	v_pk_mul_f32 v[20:21], v[20:21], v[148:149] op_sel_hi:[1,0]
	v_pk_mul_f32 v[22:23], v[22:23], v[148:149] op_sel_hi:[1,0]
	v_pk_add_f32 v[120:121], v[120:121], 1.0 op_sel_hi:[1,0]
	v_pk_add_f32 v[122:123], v[122:123], 1.0 op_sel_hi:[1,0]
	v_pk_mul_f32 v[20:21], v[4:5], v[20:21]
	v_pk_mul_f32 v[22:23], v[6:7], v[22:23]
	v_pk_fma_f32 v[20:21], v[20:21], v[120:121], v[136:137]
	v_pk_fma_f32 v[22:23], v[22:23], v[122:123], v[138:139]
	v_cvt_pk_bf16_f32 v20, v20, v21
	v_cvt_pk_bf16_f32 v21, v22, v23
	global_store_dwordx2 v48, v[20:21], s[14:15] offset:512
	v_pk_mul_f32 v[24:25], v[24:25], v[148:149] op_sel_hi:[1,0]
	v_pk_mul_f32 v[26:27], v[26:27], v[148:149] op_sel_hi:[1,0]
	v_pk_add_f32 v[124:125], v[124:125], 1.0 op_sel_hi:[1,0]
	v_pk_add_f32 v[126:127], v[126:127], 1.0 op_sel_hi:[1,0]
	v_pk_mul_f32 v[24:25], v[8:9], v[24:25]
	v_pk_mul_f32 v[26:27], v[10:11], v[26:27]
	v_pk_fma_f32 v[24:25], v[24:25], v[124:125], v[140:141]
	v_pk_fma_f32 v[26:27], v[26:27], v[126:127], v[142:143]
	v_cvt_pk_bf16_f32 v24, v24, v25
	v_cvt_pk_bf16_f32 v25, v26, v27
	global_store_dwordx2 v48, v[24:25], s[14:15] offset:1024
	v_pk_mul_f32 v[28:29], v[28:29], v[148:149] op_sel_hi:[1,0]
	v_pk_mul_f32 v[30:31], v[30:31], v[148:149] op_sel_hi:[1,0]
	v_pk_add_f32 v[128:129], v[128:129], 1.0 op_sel_hi:[1,0]
	v_pk_add_f32 v[130:131], v[130:131], 1.0 op_sel_hi:[1,0]
	v_pk_mul_f32 v[28:29], v[12:13], v[28:29]
	v_pk_mul_f32 v[30:31], v[14:15], v[30:31]
	v_pk_fma_f32 v[28:29], v[28:29], v[128:129], v[144:145]
	v_pk_fma_f32 v[30:31], v[30:31], v[130:131], v[146:147]
	v_cvt_pk_bf16_f32 v28, v28, v29
	v_cvt_pk_bf16_f32 v29, v30, v31
	global_store_dwordx2 v48, v[28:29], s[14:15] offset:1536
	s_add_u32 s14, s14, 0x400000
	s_addc_u32 s15, s15, 0
	global_load_dwordx4 v[16:19], v56, s[0:1] nt
	global_load_dwordx4 v[20:23], v56, s[0:1] offset:1024 nt
	global_load_dwordx4 v[24:27], v56, s[0:1] offset:2048 nt
	global_load_dwordx4 v[28:31], v56, s[0:1] offset:3072 nt
	s_add_u32 s0, s0, 0x800000
	s_addc_u32 s1, s1, 0
	global_load_dwordx4 v[132:135], v56, s[10:11]
	global_load_dwordx4 v[136:139], v56, s[10:11] offset:1024
	global_load_dwordx4 v[140:143], v56, s[10:11] offset:2048
	global_load_dwordx4 v[144:147], v56, s[10:11] offset:3072
	global_load_dwordx4 v[116:119], v56, s[12:13]
	global_load_dwordx4 v[120:123], v56, s[12:13] offset:1024
	global_load_dwordx4 v[124:127], v56, s[12:13] offset:2048
	global_load_dwordx4 v[128:131], v56, s[12:13] offset:3072
	s_add_u32 s10, s10, 0x6000
	s_addc_u32 s11, s11, 0
	s_add_u32 s12, s12, 0x6000
	s_addc_u32 s13, s13, 0
	s_waitcnt vmcnt(40)
	v_pk_mul_f32 v[58:59], v[32:33], v[32:33]
	v_pk_fma_f32 v[58:59], v[34:35], v[34:35], v[58:59]
	v_pk_fma_f32 v[58:59], v[36:37], v[36:37], v[58:59]
	v_pk_fma_f32 v[58:59], v[38:39], v[38:39], v[58:59]
	v_pk_fma_f32 v[58:59], v[40:41], v[40:41], v[58:59]
	v_pk_fma_f32 v[58:59], v[42:43], v[42:43], v[58:59]
	v_pk_fma_f32 v[58:59], v[44:45], v[44:45], v[58:59]
	v_pk_fma_f32 v[58:59], v[46:47], v[46:47], v[58:59]
	v_add_f32_e32 v60, v58, v59
	s_nop 1
	v_add_f32_dpp v61, v60, v60 quad_perm:[1,0,3,2] row_mask:0xf bank_mask:0xf
	s_nop 1
	v_add_f32_dpp v60, v61, v61 quad_perm:[2,3,0,1] row_mask:0xf bank_mask:0xf
	s_nop 1
	v_add_f32_dpp v61, v60, v60 row_half_mirror row_mask:0xf bank_mask:0xf
	s_nop 1
	v_add_f32_dpp v60, v61, v61 row_mirror row_mask:0xf bank_mask:0xf
	v_mov_b32_e32 v61, v60
	s_nop 1
	v_add_f32_dpp v61, v60, v60 row_bcast:15 row_mask:0xa bank_mask:0xf
	s_nop 1
	v_mov_b32_e32 v60, v61
	s_nop 1
	v_add_f32_dpp v60, v61, v61 row_bcast:31 row_mask:0xc bank_mask:0xf
	s_nop 1
	v_readlane_b32 s16, v60, 63
	s_nop 1
	v_mov_b32_e32 v148, s16
	v_fmamk_f32 v148, v148, 0x3a800000, v66
	v_rsq_f32_e32 v148, v148
	s_nop 0
	s_waitcnt vmcnt(16)
	v_pk_mul_f32 v[32:33], v[32:33], v[148:149] op_sel_hi:[1,0]
	v_pk_mul_f32 v[34:35], v[34:35], v[148:149] op_sel_hi:[1,0]
	v_pk_add_f32 v[84:85], v[84:85], 1.0 op_sel_hi:[1,0]
	v_pk_add_f32 v[86:87], v[86:87], 1.0 op_sel_hi:[1,0]
	v_pk_mul_f32 v[32:33], v[0:1], v[32:33]
	v_pk_mul_f32 v[34:35], v[2:3], v[34:35]
	v_pk_fma_f32 v[32:33], v[32:33], v[84:85], v[100:101]
	v_pk_fma_f32 v[34:35], v[34:35], v[86:87], v[102:103]
	v_cvt_pk_bf16_f32 v32, v32, v33
	v_cvt_pk_bf16_f32 v33, v34, v35
	global_store_dwordx2 v48, v[32:33], s[14:15]
	v_pk_mul_f32 v[36:37], v[36:37], v[148:149] op_sel_hi:[1,0]
	v_pk_mul_f32 v[38:39], v[38:39], v[148:149] op_sel_hi:[1,0]
	v_pk_add_f32 v[88:89], v[88:89], 1.0 op_sel_hi:[1,0]
	v_pk_add_f32 v[90:91], v[90:91], 1.0 op_sel_hi:[1,0]
	v_pk_mul_f32 v[36:37], v[4:5], v[36:37]
	v_pk_mul_f32 v[38:39], v[6:7], v[38:39]
	v_pk_fma_f32 v[36:37], v[36:37], v[88:89], v[104:105]
	v_pk_fma_f32 v[38:39], v[38:39], v[90:91], v[106:107]
	v_cvt_pk_bf16_f32 v36, v36, v37
	v_cvt_pk_bf16_f32 v37, v38, v39
	global_store_dwordx2 v48, v[36:37], s[14:15] offset:512
	v_pk_mul_f32 v[40:41], v[40:41], v[148:149] op_sel_hi:[1,0]
	v_pk_mul_f32 v[42:43], v[42:43], v[148:149] op_sel_hi:[1,0]
	v_pk_add_f32 v[92:93], v[92:93], 1.0 op_sel_hi:[1,0]
	v_pk_add_f32 v[94:95], v[94:95], 1.0 op_sel_hi:[1,0]
	v_pk_mul_f32 v[40:41], v[8:9], v[40:41]
	v_pk_mul_f32 v[42:43], v[10:11], v[42:43]
	v_pk_fma_f32 v[40:41], v[40:41], v[92:93], v[108:109]
	v_pk_fma_f32 v[42:43], v[42:43], v[94:95], v[110:111]
	v_cvt_pk_bf16_f32 v40, v40, v41
	v_cvt_pk_bf16_f32 v41, v42, v43
	global_store_dwordx2 v48, v[40:41], s[14:15] offset:1024
	v_pk_mul_f32 v[44:45], v[44:45], v[148:149] op_sel_hi:[1,0]
	v_pk_mul_f32 v[46:47], v[46:47], v[148:149] op_sel_hi:[1,0]
	v_pk_add_f32 v[96:97], v[96:97], 1.0 op_sel_hi:[1,0]
	v_pk_add_f32 v[98:99], v[98:99], 1.0 op_sel_hi:[1,0]
	v_pk_mul_f32 v[44:45], v[12:13], v[44:45]
	v_pk_mul_f32 v[46:47], v[14:15], v[46:47]
	v_pk_fma_f32 v[44:45], v[44:45], v[96:97], v[112:113]
	v_pk_fma_f32 v[46:47], v[46:47], v[98:99], v[114:115]
	v_cvt_pk_bf16_f32 v44, v44, v45
	v_cvt_pk_bf16_f32 v45, v46, v47
	global_store_dwordx2 v48, v[44:45], s[14:15] offset:1536
	s_add_u32 s14, s14, 0x400000
	s_addc_u32 s15, s15, 0
	global_load_dwordx4 v[32:35], v56, s[0:1] nt
	global_load_dwordx4 v[36:39], v56, s[0:1] offset:1024 nt
	global_load_dwordx4 v[40:43], v56, s[0:1] offset:2048 nt
	global_load_dwordx4 v[44:47], v56, s[0:1] offset:3072 nt
	s_add_u32 s0, s0, 0x800000
	s_addc_u32 s1, s1, 0
	global_load_dwordx4 v[100:103], v56, s[10:11]
	global_load_dwordx4 v[104:107], v56, s[10:11] offset:1024
	global_load_dwordx4 v[108:111], v56, s[10:11] offset:2048
	global_load_dwordx4 v[112:115], v56, s[10:11] offset:3072
	global_load_dwordx4 v[84:87], v56, s[12:13]
	global_load_dwordx4 v[88:91], v56, s[12:13] offset:1024
	global_load_dwordx4 v[92:95], v56, s[12:13] offset:2048
	global_load_dwordx4 v[96:99], v56, s[12:13] offset:3072
	s_add_u32 s10, s10, 0x6000
	s_addc_u32 s11, s11, 0
	s_add_u32 s12, s12, 0x6000
	s_addc_u32 s13, s13, 0
	s_waitcnt vmcnt(40)
	v_pk_mul_f32 v[58:59], v[68:69], v[68:69]
	v_pk_fma_f32 v[58:59], v[70:71], v[70:71], v[58:59]
	v_pk_fma_f32 v[58:59], v[72:73], v[72:73], v[58:59]
	v_pk_fma_f32 v[58:59], v[74:75], v[74:75], v[58:59]
	v_pk_fma_f32 v[58:59], v[76:77], v[76:77], v[58:59]
	v_pk_fma_f32 v[58:59], v[78:79], v[78:79], v[58:59]
	v_pk_fma_f32 v[58:59], v[80:81], v[80:81], v[58:59]
	v_pk_fma_f32 v[58:59], v[82:83], v[82:83], v[58:59]
	v_add_f32_e32 v60, v58, v59
	s_nop 1
	v_add_f32_dpp v61, v60, v60 quad_perm:[1,0,3,2] row_mask:0xf bank_mask:0xf
	s_nop 1
	v_add_f32_dpp v60, v61, v61 quad_perm:[2,3,0,1] row_mask:0xf bank_mask:0xf
	s_nop 1
	v_add_f32_dpp v61, v60, v60 row_half_mirror row_mask:0xf bank_mask:0xf
	s_nop 1
	v_add_f32_dpp v60, v61, v61 row_mirror row_mask:0xf bank_mask:0xf
	v_mov_b32_e32 v61, v60
	s_nop 1
	v_add_f32_dpp v61, v60, v60 row_bcast:15 row_mask:0xa bank_mask:0xf
	s_nop 1
	v_mov_b32_e32 v60, v61
	s_nop 1
	v_add_f32_dpp v60, v61, v61 row_bcast:31 row_mask:0xc bank_mask:0xf
	s_nop 1
	v_readlane_b32 s16, v60, 63
	s_nop 1
	v_mov_b32_e32 v148, s16
	v_fmamk_f32 v148, v148, 0x3a800000, v66
	v_rsq_f32_e32 v148, v148
	s_nop 0
	s_waitcnt vmcnt(16)
	v_pk_mul_f32 v[68:69], v[68:69], v[148:149] op_sel_hi:[1,0]
	v_pk_mul_f32 v[70:71], v[70:71], v[148:149] op_sel_hi:[1,0]
	v_pk_add_f32 v[116:117], v[116:117], 1.0 op_sel_hi:[1,0]
	v_pk_add_f32 v[118:119], v[118:119], 1.0 op_sel_hi:[1,0]
	v_pk_mul_f32 v[68:69], v[0:1], v[68:69]
	v_pk_mul_f32 v[70:71], v[2:3], v[70:71]
	v_pk_fma_f32 v[68:69], v[68:69], v[116:117], v[132:133]
	v_pk_fma_f32 v[70:71], v[70:71], v[118:119], v[134:135]
	v_cvt_pk_bf16_f32 v68, v68, v69
	v_cvt_pk_bf16_f32 v69, v70, v71
	global_store_dwordx2 v48, v[68:69], s[14:15]
	v_pk_mul_f32 v[72:73], v[72:73], v[148:149] op_sel_hi:[1,0]
	v_pk_mul_f32 v[74:75], v[74:75], v[148:149] op_sel_hi:[1,0]
	v_pk_add_f32 v[120:121], v[120:121], 1.0 op_sel_hi:[1,0]
	v_pk_add_f32 v[122:123], v[122:123], 1.0 op_sel_hi:[1,0]
	v_pk_mul_f32 v[72:73], v[4:5], v[72:73]
	v_pk_mul_f32 v[74:75], v[6:7], v[74:75]
	v_pk_fma_f32 v[72:73], v[72:73], v[120:121], v[136:137]
	v_pk_fma_f32 v[74:75], v[74:75], v[122:123], v[138:139]
	v_cvt_pk_bf16_f32 v72, v72, v73
	v_cvt_pk_bf16_f32 v73, v74, v75
	global_store_dwordx2 v48, v[72:73], s[14:15] offset:512
	v_pk_mul_f32 v[76:77], v[76:77], v[148:149] op_sel_hi:[1,0]
	v_pk_mul_f32 v[78:79], v[78:79], v[148:149] op_sel_hi:[1,0]
	v_pk_add_f32 v[124:125], v[124:125], 1.0 op_sel_hi:[1,0]
	v_pk_add_f32 v[126:127], v[126:127], 1.0 op_sel_hi:[1,0]
	v_pk_mul_f32 v[76:77], v[8:9], v[76:77]
	v_pk_mul_f32 v[78:79], v[10:11], v[78:79]
	v_pk_fma_f32 v[76:77], v[76:77], v[124:125], v[140:141]
	v_pk_fma_f32 v[78:79], v[78:79], v[126:127], v[142:143]
	v_cvt_pk_bf16_f32 v76, v76, v77
	v_cvt_pk_bf16_f32 v77, v78, v79
	global_store_dwordx2 v48, v[76:77], s[14:15] offset:1024
	v_pk_mul_f32 v[80:81], v[80:81], v[148:149] op_sel_hi:[1,0]
	v_pk_mul_f32 v[82:83], v[82:83], v[148:149] op_sel_hi:[1,0]
	v_pk_add_f32 v[128:129], v[128:129], 1.0 op_sel_hi:[1,0]
	v_pk_add_f32 v[130:131], v[130:131], 1.0 op_sel_hi:[1,0]
	v_pk_mul_f32 v[80:81], v[12:13], v[80:81]
	v_pk_mul_f32 v[82:83], v[14:15], v[82:83]
	v_pk_fma_f32 v[80:81], v[80:81], v[128:129], v[144:145]
	v_pk_fma_f32 v[82:83], v[82:83], v[130:131], v[146:147]
	v_cvt_pk_bf16_f32 v80, v80, v81
	v_cvt_pk_bf16_f32 v81, v82, v83
	global_store_dwordx2 v48, v[80:81], s[14:15] offset:1536
	s_add_u32 s14, s14, 0x400000
	s_addc_u32 s15, s15, 0
	global_load_dwordx4 v[68:71], v56, s[0:1] nt
	global_load_dwordx4 v[72:75], v56, s[0:1] offset:1024 nt
	global_load_dwordx4 v[76:79], v56, s[0:1] offset:2048 nt
	global_load_dwordx4 v[80:83], v56, s[0:1] offset:3072 nt
	s_add_u32 s0, s0, 0x800000
	s_addc_u32 s1, s1, 0
	global_load_dwordx4 v[132:135], v56, s[10:11]
	global_load_dwordx4 v[136:139], v56, s[10:11] offset:1024
	global_load_dwordx4 v[140:143], v56, s[10:11] offset:2048
	global_load_dwordx4 v[144:147], v56, s[10:11] offset:3072
	global_load_dwordx4 v[116:119], v56, s[12:13]
	global_load_dwordx4 v[120:123], v56, s[12:13] offset:1024
	global_load_dwordx4 v[124:127], v56, s[12:13] offset:2048
	global_load_dwordx4 v[128:131], v56, s[12:13] offset:3072
	s_add_u32 s10, s10, 0x6000
	s_addc_u32 s11, s11, 0
	s_add_u32 s12, s12, 0x6000
	s_addc_u32 s13, s13, 0
	s_waitcnt vmcnt(40)
	v_pk_mul_f32 v[58:59], v[16:17], v[16:17]
	v_pk_fma_f32 v[58:59], v[18:19], v[18:19], v[58:59]
	v_pk_fma_f32 v[58:59], v[20:21], v[20:21], v[58:59]
	v_pk_fma_f32 v[58:59], v[22:23], v[22:23], v[58:59]
	v_pk_fma_f32 v[58:59], v[24:25], v[24:25], v[58:59]
	v_pk_fma_f32 v[58:59], v[26:27], v[26:27], v[58:59]
	v_pk_fma_f32 v[58:59], v[28:29], v[28:29], v[58:59]
	v_pk_fma_f32 v[58:59], v[30:31], v[30:31], v[58:59]
	v_add_f32_e32 v60, v58, v59
	s_nop 1
	v_add_f32_dpp v61, v60, v60 quad_perm:[1,0,3,2] row_mask:0xf bank_mask:0xf
	s_nop 1
	v_add_f32_dpp v60, v61, v61 quad_perm:[2,3,0,1] row_mask:0xf bank_mask:0xf
	s_nop 1
	v_add_f32_dpp v61, v60, v60 row_half_mirror row_mask:0xf bank_mask:0xf
	s_nop 1
	v_add_f32_dpp v60, v61, v61 row_mirror row_mask:0xf bank_mask:0xf
	v_mov_b32_e32 v61, v60
	s_nop 1
	v_add_f32_dpp v61, v60, v60 row_bcast:15 row_mask:0xa bank_mask:0xf
	s_nop 1
	v_mov_b32_e32 v60, v61
	s_nop 1
	v_add_f32_dpp v60, v61, v61 row_bcast:31 row_mask:0xc bank_mask:0xf
	s_nop 1
	v_readlane_b32 s16, v60, 63
	s_nop 1
	v_mov_b32_e32 v148, s16
	v_fmamk_f32 v148, v148, 0x3a800000, v66
	v_rsq_f32_e32 v148, v148
	s_nop 0
	s_waitcnt vmcnt(16)
	v_pk_mul_f32 v[16:17], v[16:17], v[148:149] op_sel_hi:[1,0]
	v_pk_mul_f32 v[18:19], v[18:19], v[148:149] op_sel_hi:[1,0]
	v_pk_add_f32 v[84:85], v[84:85], 1.0 op_sel_hi:[1,0]
	v_pk_add_f32 v[86:87], v[86:87], 1.0 op_sel_hi:[1,0]
	v_pk_mul_f32 v[16:17], v[0:1], v[16:17]
	v_pk_mul_f32 v[18:19], v[2:3], v[18:19]
	v_pk_fma_f32 v[16:17], v[16:17], v[84:85], v[100:101]
	v_pk_fma_f32 v[18:19], v[18:19], v[86:87], v[102:103]
	v_cvt_pk_bf16_f32 v16, v16, v17
	v_cvt_pk_bf16_f32 v17, v18, v19
	global_store_dwordx2 v48, v[16:17], s[14:15]
	v_pk_mul_f32 v[20:21], v[20:21], v[148:149] op_sel_hi:[1,0]
	v_pk_mul_f32 v[22:23], v[22:23], v[148:149] op_sel_hi:[1,0]
	v_pk_add_f32 v[88:89], v[88:89], 1.0 op_sel_hi:[1,0]
	v_pk_add_f32 v[90:91], v[90:91], 1.0 op_sel_hi:[1,0]
	v_pk_mul_f32 v[20:21], v[4:5], v[20:21]
	v_pk_mul_f32 v[22:23], v[6:7], v[22:23]
	v_pk_fma_f32 v[20:21], v[20:21], v[88:89], v[104:105]
	v_pk_fma_f32 v[22:23], v[22:23], v[90:91], v[106:107]
	v_cvt_pk_bf16_f32 v20, v20, v21
	v_cvt_pk_bf16_f32 v21, v22, v23
	global_store_dwordx2 v48, v[20:21], s[14:15] offset:512
	v_pk_mul_f32 v[24:25], v[24:25], v[148:149] op_sel_hi:[1,0]
	v_pk_mul_f32 v[26:27], v[26:27], v[148:149] op_sel_hi:[1,0]
	v_pk_add_f32 v[92:93], v[92:93], 1.0 op_sel_hi:[1,0]
	v_pk_add_f32 v[94:95], v[94:95], 1.0 op_sel_hi:[1,0]
	v_pk_mul_f32 v[24:25], v[8:9], v[24:25]
	v_pk_mul_f32 v[26:27], v[10:11], v[26:27]
	v_pk_fma_f32 v[24:25], v[24:25], v[92:93], v[108:109]
	v_pk_fma_f32 v[26:27], v[26:27], v[94:95], v[110:111]
	v_cvt_pk_bf16_f32 v24, v24, v25
	v_cvt_pk_bf16_f32 v25, v26, v27
	global_store_dwordx2 v48, v[24:25], s[14:15] offset:1024
	v_pk_mul_f32 v[28:29], v[28:29], v[148:149] op_sel_hi:[1,0]
	v_pk_mul_f32 v[30:31], v[30:31], v[148:149] op_sel_hi:[1,0]
	v_pk_add_f32 v[96:97], v[96:97], 1.0 op_sel_hi:[1,0]
	v_pk_add_f32 v[98:99], v[98:99], 1.0 op_sel_hi:[1,0]
	v_pk_mul_f32 v[28:29], v[12:13], v[28:29]
	v_pk_mul_f32 v[30:31], v[14:15], v[30:31]
	v_pk_fma_f32 v[28:29], v[28:29], v[96:97], v[112:113]
	v_pk_fma_f32 v[30:31], v[30:31], v[98:99], v[114:115]
	v_cvt_pk_bf16_f32 v28, v28, v29
	v_cvt_pk_bf16_f32 v29, v30, v31
	global_store_dwordx2 v48, v[28:29], s[14:15] offset:1536
	s_add_u32 s14, s14, 0x400000
	s_addc_u32 s15, s15, 0
	global_load_dwordx4 v[16:19], v56, s[0:1] nt
	global_load_dwordx4 v[20:23], v56, s[0:1] offset:1024 nt
	global_load_dwordx4 v[24:27], v56, s[0:1] offset:2048 nt
	global_load_dwordx4 v[28:31], v56, s[0:1] offset:3072 nt
	s_add_u32 s0, s0, 0x800000
	s_addc_u32 s1, s1, 0
	global_load_dwordx4 v[100:103], v56, s[10:11]
	global_load_dwordx4 v[104:107], v56, s[10:11] offset:1024
	global_load_dwordx4 v[108:111], v56, s[10:11] offset:2048
	global_load_dwordx4 v[112:115], v56, s[10:11] offset:3072
	global_load_dwordx4 v[84:87], v56, s[12:13]
	global_load_dwordx4 v[88:91], v56, s[12:13] offset:1024
	global_load_dwordx4 v[92:95], v56, s[12:13] offset:2048
	global_load_dwordx4 v[96:99], v56, s[12:13] offset:3072
	s_add_u32 s10, s10, 0x6000
	s_addc_u32 s11, s11, 0
	s_add_u32 s12, s12, 0x6000
	s_addc_u32 s13, s13, 0
	s_waitcnt vmcnt(40)
	v_pk_mul_f32 v[58:59], v[32:33], v[32:33]
	v_pk_fma_f32 v[58:59], v[34:35], v[34:35], v[58:59]
	v_pk_fma_f32 v[58:59], v[36:37], v[36:37], v[58:59]
	v_pk_fma_f32 v[58:59], v[38:39], v[38:39], v[58:59]
	v_pk_fma_f32 v[58:59], v[40:41], v[40:41], v[58:59]
	v_pk_fma_f32 v[58:59], v[42:43], v[42:43], v[58:59]
	v_pk_fma_f32 v[58:59], v[44:45], v[44:45], v[58:59]
	v_pk_fma_f32 v[58:59], v[46:47], v[46:47], v[58:59]
	v_add_f32_e32 v60, v58, v59
	s_nop 1
	v_add_f32_dpp v61, v60, v60 quad_perm:[1,0,3,2] row_mask:0xf bank_mask:0xf
	s_nop 1
	v_add_f32_dpp v60, v61, v61 quad_perm:[2,3,0,1] row_mask:0xf bank_mask:0xf
	s_nop 1
	v_add_f32_dpp v61, v60, v60 row_half_mirror row_mask:0xf bank_mask:0xf
	s_nop 1
	v_add_f32_dpp v60, v61, v61 row_mirror row_mask:0xf bank_mask:0xf
	v_mov_b32_e32 v61, v60
	s_nop 1
	v_add_f32_dpp v61, v60, v60 row_bcast:15 row_mask:0xa bank_mask:0xf
	s_nop 1
	v_mov_b32_e32 v60, v61
	s_nop 1
	v_add_f32_dpp v60, v61, v61 row_bcast:31 row_mask:0xc bank_mask:0xf
	s_nop 1
	v_readlane_b32 s16, v60, 63
	s_nop 1
	v_mov_b32_e32 v148, s16
	v_fmamk_f32 v148, v148, 0x3a800000, v66
	v_rsq_f32_e32 v148, v148
	s_nop 0
	s_waitcnt vmcnt(16)
	v_pk_mul_f32 v[32:33], v[32:33], v[148:149] op_sel_hi:[1,0]
	v_pk_mul_f32 v[34:35], v[34:35], v[148:149] op_sel_hi:[1,0]
	v_pk_add_f32 v[116:117], v[116:117], 1.0 op_sel_hi:[1,0]
	v_pk_add_f32 v[118:119], v[118:119], 1.0 op_sel_hi:[1,0]
	v_pk_mul_f32 v[32:33], v[0:1], v[32:33]
	v_pk_mul_f32 v[34:35], v[2:3], v[34:35]
	v_pk_fma_f32 v[32:33], v[32:33], v[116:117], v[132:133]
	v_pk_fma_f32 v[34:35], v[34:35], v[118:119], v[134:135]
	v_cvt_pk_bf16_f32 v32, v32, v33
	v_cvt_pk_bf16_f32 v33, v34, v35
	global_store_dwordx2 v48, v[32:33], s[14:15]
	v_pk_mul_f32 v[36:37], v[36:37], v[148:149] op_sel_hi:[1,0]
	v_pk_mul_f32 v[38:39], v[38:39], v[148:149] op_sel_hi:[1,0]
	v_pk_add_f32 v[120:121], v[120:121], 1.0 op_sel_hi:[1,0]
	v_pk_add_f32 v[122:123], v[122:123], 1.0 op_sel_hi:[1,0]
	v_pk_mul_f32 v[36:37], v[4:5], v[36:37]
	v_pk_mul_f32 v[38:39], v[6:7], v[38:39]
	v_pk_fma_f32 v[36:37], v[36:37], v[120:121], v[136:137]
	v_pk_fma_f32 v[38:39], v[38:39], v[122:123], v[138:139]
	v_cvt_pk_bf16_f32 v36, v36, v37
	v_cvt_pk_bf16_f32 v37, v38, v39
	global_store_dwordx2 v48, v[36:37], s[14:15] offset:512
	v_pk_mul_f32 v[40:41], v[40:41], v[148:149] op_sel_hi:[1,0]
	v_pk_mul_f32 v[42:43], v[42:43], v[148:149] op_sel_hi:[1,0]
	v_pk_add_f32 v[124:125], v[124:125], 1.0 op_sel_hi:[1,0]
	v_pk_add_f32 v[126:127], v[126:127], 1.0 op_sel_hi:[1,0]
	v_pk_mul_f32 v[40:41], v[8:9], v[40:41]
	v_pk_mul_f32 v[42:43], v[10:11], v[42:43]
	v_pk_fma_f32 v[40:41], v[40:41], v[124:125], v[140:141]
	v_pk_fma_f32 v[42:43], v[42:43], v[126:127], v[142:143]
	v_cvt_pk_bf16_f32 v40, v40, v41
	v_cvt_pk_bf16_f32 v41, v42, v43
	global_store_dwordx2 v48, v[40:41], s[14:15] offset:1024
	v_pk_mul_f32 v[44:45], v[44:45], v[148:149] op_sel_hi:[1,0]
	v_pk_mul_f32 v[46:47], v[46:47], v[148:149] op_sel_hi:[1,0]
	v_pk_add_f32 v[128:129], v[128:129], 1.0 op_sel_hi:[1,0]
	v_pk_add_f32 v[130:131], v[130:131], 1.0 op_sel_hi:[1,0]
	v_pk_mul_f32 v[44:45], v[12:13], v[44:45]
	v_pk_mul_f32 v[46:47], v[14:15], v[46:47]
	v_pk_fma_f32 v[44:45], v[44:45], v[128:129], v[144:145]
	v_pk_fma_f32 v[46:47], v[46:47], v[130:131], v[146:147]
	v_cvt_pk_bf16_f32 v44, v44, v45
	v_cvt_pk_bf16_f32 v45, v46, v47
	global_store_dwordx2 v48, v[44:45], s[14:15] offset:1536
	s_add_u32 s14, s14, 0x400000
	s_addc_u32 s15, s15, 0
	v_readlane_b32 s0, v253, 14
	v_readlane_b32 s1, v253, 15
	s_lshl_b64 s[16:17], s[4:5], 12
	s_add_u32 s0, s0, s16
	s_addc_u32 s1, s1, s17
	global_load_dwordx4 v[32:35], v56, s[0:1] nt
	global_load_dwordx4 v[36:39], v56, s[0:1] offset:1024 nt
	global_load_dwordx4 v[40:43], v56, s[0:1] offset:2048 nt
	global_load_dwordx4 v[44:47], v56, s[0:1] offset:3072 nt
	s_add_u32 s0, s0, 0x800000
	s_addc_u32 s1, s1, 0
	global_load_dwordx4 v[132:135], v56, s[10:11]
	global_load_dwordx4 v[136:139], v56, s[10:11] offset:1024
	global_load_dwordx4 v[140:143], v56, s[10:11] offset:2048
	global_load_dwordx4 v[144:147], v56, s[10:11] offset:3072
	global_load_dwordx4 v[116:119], v56, s[12:13]
	global_load_dwordx4 v[120:123], v56, s[12:13] offset:1024
	global_load_dwordx4 v[124:127], v56, s[12:13] offset:2048
	global_load_dwordx4 v[128:131], v56, s[12:13] offset:3072
	s_add_u32 s10, s10, 0x6000
	s_addc_u32 s11, s11, 0
	s_add_u32 s12, s12, 0x6000
	s_addc_u32 s13, s13, 0
	s_waitcnt vmcnt(40)
	v_pk_mul_f32 v[58:59], v[68:69], v[68:69]
	v_pk_fma_f32 v[58:59], v[70:71], v[70:71], v[58:59]
	v_pk_fma_f32 v[58:59], v[72:73], v[72:73], v[58:59]
	v_pk_fma_f32 v[58:59], v[74:75], v[74:75], v[58:59]
	v_pk_fma_f32 v[58:59], v[76:77], v[76:77], v[58:59]
	v_pk_fma_f32 v[58:59], v[78:79], v[78:79], v[58:59]
	v_pk_fma_f32 v[58:59], v[80:81], v[80:81], v[58:59]
	v_pk_fma_f32 v[58:59], v[82:83], v[82:83], v[58:59]
	v_add_f32_e32 v60, v58, v59
	s_nop 1
	v_add_f32_dpp v61, v60, v60 quad_perm:[1,0,3,2] row_mask:0xf bank_mask:0xf
	s_nop 1
	v_add_f32_dpp v60, v61, v61 quad_perm:[2,3,0,1] row_mask:0xf bank_mask:0xf
	s_nop 1
	v_add_f32_dpp v61, v60, v60 row_half_mirror row_mask:0xf bank_mask:0xf
	s_nop 1
	v_add_f32_dpp v60, v61, v61 row_mirror row_mask:0xf bank_mask:0xf
	v_mov_b32_e32 v61, v60
	s_nop 1
	v_add_f32_dpp v61, v60, v60 row_bcast:15 row_mask:0xa bank_mask:0xf
	s_nop 1
	v_mov_b32_e32 v60, v61
	s_nop 1
	v_add_f32_dpp v60, v61, v61 row_bcast:31 row_mask:0xc bank_mask:0xf
	s_nop 1
	v_readlane_b32 s16, v60, 63
	s_nop 1
	v_mov_b32_e32 v148, s16
	v_fmamk_f32 v148, v148, 0x3a800000, v66
	v_rsq_f32_e32 v148, v148
	s_nop 0
	s_waitcnt vmcnt(16)
	v_pk_mul_f32 v[68:69], v[68:69], v[148:149] op_sel_hi:[1,0]
	v_pk_mul_f32 v[70:71], v[70:71], v[148:149] op_sel_hi:[1,0]
	v_pk_add_f32 v[84:85], v[84:85], 1.0 op_sel_hi:[1,0]
	v_pk_add_f32 v[86:87], v[86:87], 1.0 op_sel_hi:[1,0]
	v_pk_mul_f32 v[68:69], v[0:1], v[68:69]
	v_pk_mul_f32 v[70:71], v[2:3], v[70:71]
	v_pk_fma_f32 v[68:69], v[68:69], v[84:85], v[100:101]
	v_pk_fma_f32 v[70:71], v[70:71], v[86:87], v[102:103]
	v_cvt_pk_bf16_f32 v68, v68, v69
	v_cvt_pk_bf16_f32 v69, v70, v71
	global_store_dwordx2 v48, v[68:69], s[14:15]
	v_pk_mul_f32 v[72:73], v[72:73], v[148:149] op_sel_hi:[1,0]
	v_pk_mul_f32 v[74:75], v[74:75], v[148:149] op_sel_hi:[1,0]
	v_pk_add_f32 v[88:89], v[88:89], 1.0 op_sel_hi:[1,0]
	v_pk_add_f32 v[90:91], v[90:91], 1.0 op_sel_hi:[1,0]
	v_pk_mul_f32 v[72:73], v[4:5], v[72:73]
	v_pk_mul_f32 v[74:75], v[6:7], v[74:75]
	v_pk_fma_f32 v[72:73], v[72:73], v[88:89], v[104:105]
	v_pk_fma_f32 v[74:75], v[74:75], v[90:91], v[106:107]
	v_cvt_pk_bf16_f32 v72, v72, v73
	v_cvt_pk_bf16_f32 v73, v74, v75
	global_store_dwordx2 v48, v[72:73], s[14:15] offset:512
	v_pk_mul_f32 v[76:77], v[76:77], v[148:149] op_sel_hi:[1,0]
	v_pk_mul_f32 v[78:79], v[78:79], v[148:149] op_sel_hi:[1,0]
	v_pk_add_f32 v[92:93], v[92:93], 1.0 op_sel_hi:[1,0]
	v_pk_add_f32 v[94:95], v[94:95], 1.0 op_sel_hi:[1,0]
	v_pk_mul_f32 v[76:77], v[8:9], v[76:77]
	v_pk_mul_f32 v[78:79], v[10:11], v[78:79]
	v_pk_fma_f32 v[76:77], v[76:77], v[92:93], v[108:109]
	v_pk_fma_f32 v[78:79], v[78:79], v[94:95], v[110:111]
	v_cvt_pk_bf16_f32 v76, v76, v77
	v_cvt_pk_bf16_f32 v77, v78, v79
	global_store_dwordx2 v48, v[76:77], s[14:15] offset:1024
	v_pk_mul_f32 v[80:81], v[80:81], v[148:149] op_sel_hi:[1,0]
	v_pk_mul_f32 v[82:83], v[82:83], v[148:149] op_sel_hi:[1,0]
	v_pk_add_f32 v[96:97], v[96:97], 1.0 op_sel_hi:[1,0]
	v_pk_add_f32 v[98:99], v[98:99], 1.0 op_sel_hi:[1,0]
	v_pk_mul_f32 v[80:81], v[12:13], v[80:81]
	v_pk_mul_f32 v[82:83], v[14:15], v[82:83]
	v_pk_fma_f32 v[80:81], v[80:81], v[96:97], v[112:113]
	v_pk_fma_f32 v[82:83], v[82:83], v[98:99], v[114:115]
	v_cvt_pk_bf16_f32 v80, v80, v81
	v_cvt_pk_bf16_f32 v81, v82, v83
	global_store_dwordx2 v48, v[80:81], s[14:15] offset:1536
	s_add_u32 s14, s14, 0x400000
	s_addc_u32 s15, s15, 0
	global_load_dwordx4 v[68:71], v56, s[0:1] nt
	global_load_dwordx4 v[72:75], v56, s[0:1] offset:1024 nt
	global_load_dwordx4 v[76:79], v56, s[0:1] offset:2048 nt
	global_load_dwordx4 v[80:83], v56, s[0:1] offset:3072 nt
	s_add_u32 s0, s0, 0x800000
	s_addc_u32 s1, s1, 0
	global_load_dwordx4 v[100:103], v56, s[10:11]
	global_load_dwordx4 v[104:107], v56, s[10:11] offset:1024
	global_load_dwordx4 v[108:111], v56, s[10:11] offset:2048
	global_load_dwordx4 v[112:115], v56, s[10:11] offset:3072
	global_load_dwordx4 v[84:87], v56, s[12:13]
	global_load_dwordx4 v[88:91], v56, s[12:13] offset:1024
	global_load_dwordx4 v[92:95], v56, s[12:13] offset:2048
	global_load_dwordx4 v[96:99], v56, s[12:13] offset:3072
	s_waitcnt vmcnt(40)
	v_pk_mul_f32 v[58:59], v[16:17], v[16:17]
	v_pk_fma_f32 v[58:59], v[18:19], v[18:19], v[58:59]
	v_pk_fma_f32 v[58:59], v[20:21], v[20:21], v[58:59]
	v_pk_fma_f32 v[58:59], v[22:23], v[22:23], v[58:59]
	v_pk_fma_f32 v[58:59], v[24:25], v[24:25], v[58:59]
	v_pk_fma_f32 v[58:59], v[26:27], v[26:27], v[58:59]
	v_pk_fma_f32 v[58:59], v[28:29], v[28:29], v[58:59]
	v_pk_fma_f32 v[58:59], v[30:31], v[30:31], v[58:59]
	v_add_f32_e32 v60, v58, v59
	s_nop 1
	v_add_f32_dpp v61, v60, v60 quad_perm:[1,0,3,2] row_mask:0xf bank_mask:0xf
	s_nop 1
	v_add_f32_dpp v60, v61, v61 quad_perm:[2,3,0,1] row_mask:0xf bank_mask:0xf
	s_nop 1
	v_add_f32_dpp v61, v60, v60 row_half_mirror row_mask:0xf bank_mask:0xf
	s_nop 1
	v_add_f32_dpp v60, v61, v61 row_mirror row_mask:0xf bank_mask:0xf
	v_mov_b32_e32 v61, v60
	s_nop 1
	v_add_f32_dpp v61, v60, v60 row_bcast:15 row_mask:0xa bank_mask:0xf
	s_nop 1
	v_mov_b32_e32 v60, v61
	s_nop 1
	v_add_f32_dpp v60, v61, v61 row_bcast:31 row_mask:0xc bank_mask:0xf
	s_nop 1
	v_readlane_b32 s16, v60, 63
	s_nop 1
	v_mov_b32_e32 v148, s16
	v_fmamk_f32 v148, v148, 0x3a800000, v66
	v_rsq_f32_e32 v148, v148
	s_nop 0
	s_waitcnt vmcnt(16)
	v_pk_mul_f32 v[16:17], v[16:17], v[148:149] op_sel_hi:[1,0]
	v_pk_mul_f32 v[18:19], v[18:19], v[148:149] op_sel_hi:[1,0]
	v_pk_add_f32 v[116:117], v[116:117], 1.0 op_sel_hi:[1,0]
	v_pk_add_f32 v[118:119], v[118:119], 1.0 op_sel_hi:[1,0]
	v_pk_mul_f32 v[16:17], v[0:1], v[16:17]
	v_pk_mul_f32 v[18:19], v[2:3], v[18:19]
	v_pk_fma_f32 v[16:17], v[16:17], v[116:117], v[132:133]
	v_pk_fma_f32 v[18:19], v[18:19], v[118:119], v[134:135]
	v_cvt_pk_bf16_f32 v16, v16, v17
	v_cvt_pk_bf16_f32 v17, v18, v19
	global_store_dwordx2 v48, v[16:17], s[14:15]
	v_pk_mul_f32 v[20:21], v[20:21], v[148:149] op_sel_hi:[1,0]
	v_pk_mul_f32 v[22:23], v[22:23], v[148:149] op_sel_hi:[1,0]
	v_pk_add_f32 v[120:121], v[120:121], 1.0 op_sel_hi:[1,0]
	v_pk_add_f32 v[122:123], v[122:123], 1.0 op_sel_hi:[1,0]
	v_pk_mul_f32 v[20:21], v[4:5], v[20:21]
	v_pk_mul_f32 v[22:23], v[6:7], v[22:23]
	v_pk_fma_f32 v[20:21], v[20:21], v[120:121], v[136:137]
	v_pk_fma_f32 v[22:23], v[22:23], v[122:123], v[138:139]
	v_cvt_pk_bf16_f32 v20, v20, v21
	v_cvt_pk_bf16_f32 v21, v22, v23
	global_store_dwordx2 v48, v[20:21], s[14:15] offset:512
	v_pk_mul_f32 v[24:25], v[24:25], v[148:149] op_sel_hi:[1,0]
	v_pk_mul_f32 v[26:27], v[26:27], v[148:149] op_sel_hi:[1,0]
	v_pk_add_f32 v[124:125], v[124:125], 1.0 op_sel_hi:[1,0]
	v_pk_add_f32 v[126:127], v[126:127], 1.0 op_sel_hi:[1,0]
	v_pk_mul_f32 v[24:25], v[8:9], v[24:25]
	v_pk_mul_f32 v[26:27], v[10:11], v[26:27]
	v_pk_fma_f32 v[24:25], v[24:25], v[124:125], v[140:141]
	v_pk_fma_f32 v[26:27], v[26:27], v[126:127], v[142:143]
	v_cvt_pk_bf16_f32 v24, v24, v25
	v_cvt_pk_bf16_f32 v25, v26, v27
	global_store_dwordx2 v48, v[24:25], s[14:15] offset:1024
	v_pk_mul_f32 v[28:29], v[28:29], v[148:149] op_sel_hi:[1,0]
	v_pk_mul_f32 v[30:31], v[30:31], v[148:149] op_sel_hi:[1,0]
	v_pk_add_f32 v[128:129], v[128:129], 1.0 op_sel_hi:[1,0]
	v_pk_add_f32 v[130:131], v[130:131], 1.0 op_sel_hi:[1,0]
	v_pk_mul_f32 v[28:29], v[12:13], v[28:29]
	v_pk_mul_f32 v[30:31], v[14:15], v[30:31]
	v_pk_fma_f32 v[28:29], v[28:29], v[128:129], v[144:145]
	v_pk_fma_f32 v[30:31], v[30:31], v[130:131], v[146:147]
	v_cvt_pk_bf16_f32 v28, v28, v29
	v_cvt_pk_bf16_f32 v29, v30, v31
	global_store_dwordx2 v48, v[28:29], s[14:15] offset:1536
	s_add_u32 s14, s14, 0x400000
	s_addc_u32 s15, s15, 0
	global_load_dwordx4 v[132:135], v56, s[10:11]
	global_load_dwordx4 v[136:139], v56, s[10:11] offset:1024
	global_load_dwordx4 v[140:143], v56, s[10:11] offset:2048
	global_load_dwordx4 v[144:147], v56, s[10:11] offset:3072
	global_load_dwordx4 v[116:119], v56, s[12:13]
	global_load_dwordx4 v[120:123], v56, s[12:13] offset:1024
	global_load_dwordx4 v[124:127], v56, s[12:13] offset:2048
	global_load_dwordx4 v[128:131], v56, s[12:13] offset:3072
	s_waitcnt vmcnt(36)
	v_pk_mul_f32 v[58:59], v[32:33], v[32:33]
	v_pk_fma_f32 v[58:59], v[34:35], v[34:35], v[58:59]
	v_pk_fma_f32 v[58:59], v[36:37], v[36:37], v[58:59]
	v_pk_fma_f32 v[58:59], v[38:39], v[38:39], v[58:59]
	v_pk_fma_f32 v[58:59], v[40:41], v[40:41], v[58:59]
	v_pk_fma_f32 v[58:59], v[42:43], v[42:43], v[58:59]
	v_pk_fma_f32 v[58:59], v[44:45], v[44:45], v[58:59]
	v_pk_fma_f32 v[58:59], v[46:47], v[46:47], v[58:59]
	v_add_f32_e32 v60, v58, v59
	s_nop 1
	v_add_f32_dpp v61, v60, v60 quad_perm:[1,0,3,2] row_mask:0xf bank_mask:0xf
	s_nop 1
	v_add_f32_dpp v60, v61, v61 quad_perm:[2,3,0,1] row_mask:0xf bank_mask:0xf
	s_nop 1
	v_add_f32_dpp v61, v60, v60 row_half_mirror row_mask:0xf bank_mask:0xf
	s_nop 1
	v_add_f32_dpp v60, v61, v61 row_mirror row_mask:0xf bank_mask:0xf
	v_mov_b32_e32 v61, v60
	s_nop 1
	v_add_f32_dpp v61, v60, v60 row_bcast:15 row_mask:0xa bank_mask:0xf
	s_nop 1
	v_mov_b32_e32 v60, v61
	s_nop 1
	v_add_f32_dpp v60, v61, v61 row_bcast:31 row_mask:0xc bank_mask:0xf
	s_nop 1
	v_readlane_b32 s16, v60, 63
	s_nop 1
	v_mov_b32_e32 v148, s16
	v_fmamk_f32 v148, v148, 0x3a800000, v66
	v_rsq_f32_e32 v148, v148
	s_nop 0
	s_waitcnt vmcnt(12)
	v_pk_mul_f32 v[32:33], v[32:33], v[148:149] op_sel_hi:[1,0]
	v_pk_mul_f32 v[34:35], v[34:35], v[148:149] op_sel_hi:[1,0]
	v_pk_add_f32 v[84:85], v[84:85], 1.0 op_sel_hi:[1,0]
	v_pk_add_f32 v[86:87], v[86:87], 1.0 op_sel_hi:[1,0]
	v_pk_mul_f32 v[32:33], v[0:1], v[32:33]
	v_pk_mul_f32 v[34:35], v[2:3], v[34:35]
	v_pk_fma_f32 v[32:33], v[32:33], v[84:85], v[100:101]
	v_pk_fma_f32 v[34:35], v[34:35], v[86:87], v[102:103]
	v_cvt_pk_bf16_f32 v32, v32, v33
	v_cvt_pk_bf16_f32 v33, v34, v35
	global_store_dwordx2 v48, v[32:33], s[14:15]
	v_pk_mul_f32 v[36:37], v[36:37], v[148:149] op_sel_hi:[1,0]
	v_pk_mul_f32 v[38:39], v[38:39], v[148:149] op_sel_hi:[1,0]
	v_pk_add_f32 v[88:89], v[88:89], 1.0 op_sel_hi:[1,0]
	v_pk_add_f32 v[90:91], v[90:91], 1.0 op_sel_hi:[1,0]
	v_pk_mul_f32 v[36:37], v[4:5], v[36:37]
	v_pk_mul_f32 v[38:39], v[6:7], v[38:39]
	v_pk_fma_f32 v[36:37], v[36:37], v[88:89], v[104:105]
	v_pk_fma_f32 v[38:39], v[38:39], v[90:91], v[106:107]
	v_cvt_pk_bf16_f32 v36, v36, v37
	v_cvt_pk_bf16_f32 v37, v38, v39
	global_store_dwordx2 v48, v[36:37], s[14:15] offset:512
	v_pk_mul_f32 v[40:41], v[40:41], v[148:149] op_sel_hi:[1,0]
	v_pk_mul_f32 v[42:43], v[42:43], v[148:149] op_sel_hi:[1,0]
	v_pk_add_f32 v[92:93], v[92:93], 1.0 op_sel_hi:[1,0]
	v_pk_add_f32 v[94:95], v[94:95], 1.0 op_sel_hi:[1,0]
	v_pk_mul_f32 v[40:41], v[8:9], v[40:41]
	v_pk_mul_f32 v[42:43], v[10:11], v[42:43]
	v_pk_fma_f32 v[40:41], v[40:41], v[92:93], v[108:109]
	v_pk_fma_f32 v[42:43], v[42:43], v[94:95], v[110:111]
	v_cvt_pk_bf16_f32 v40, v40, v41
	v_cvt_pk_bf16_f32 v41, v42, v43
	global_store_dwordx2 v48, v[40:41], s[14:15] offset:1024
	v_pk_mul_f32 v[44:45], v[44:45], v[148:149] op_sel_hi:[1,0]
	v_pk_mul_f32 v[46:47], v[46:47], v[148:149] op_sel_hi:[1,0]
	v_pk_add_f32 v[96:97], v[96:97], 1.0 op_sel_hi:[1,0]
	v_pk_add_f32 v[98:99], v[98:99], 1.0 op_sel_hi:[1,0]
	v_pk_mul_f32 v[44:45], v[12:13], v[44:45]
	v_pk_mul_f32 v[46:47], v[14:15], v[46:47]
	v_pk_fma_f32 v[44:45], v[44:45], v[96:97], v[112:113]
	v_pk_fma_f32 v[46:47], v[46:47], v[98:99], v[114:115]
	v_cvt_pk_bf16_f32 v44, v44, v45
	v_cvt_pk_bf16_f32 v45, v46, v47
	global_store_dwordx2 v48, v[44:45], s[14:15] offset:1536
	s_add_u32 s14, s14, 0x400000
	s_addc_u32 s15, s15, 0
	s_waitcnt vmcnt(24)
	v_pk_mul_f32 v[58:59], v[68:69], v[68:69]
	v_pk_fma_f32 v[58:59], v[70:71], v[70:71], v[58:59]
	v_pk_fma_f32 v[58:59], v[72:73], v[72:73], v[58:59]
	v_pk_fma_f32 v[58:59], v[74:75], v[74:75], v[58:59]
	v_pk_fma_f32 v[58:59], v[76:77], v[76:77], v[58:59]
	v_pk_fma_f32 v[58:59], v[78:79], v[78:79], v[58:59]
	v_pk_fma_f32 v[58:59], v[80:81], v[80:81], v[58:59]
	v_pk_fma_f32 v[58:59], v[82:83], v[82:83], v[58:59]
	v_add_f32_e32 v60, v58, v59
	s_nop 1
	v_add_f32_dpp v61, v60, v60 quad_perm:[1,0,3,2] row_mask:0xf bank_mask:0xf
	s_nop 1
	v_add_f32_dpp v60, v61, v61 quad_perm:[2,3,0,1] row_mask:0xf bank_mask:0xf
	s_nop 1
	v_add_f32_dpp v61, v60, v60 row_half_mirror row_mask:0xf bank_mask:0xf
	s_nop 1
	v_add_f32_dpp v60, v61, v61 row_mirror row_mask:0xf bank_mask:0xf
	v_mov_b32_e32 v61, v60
	s_nop 1
	v_add_f32_dpp v61, v60, v60 row_bcast:15 row_mask:0xa bank_mask:0xf
	s_nop 1
	v_mov_b32_e32 v60, v61
	s_nop 1
	v_add_f32_dpp v60, v61, v61 row_bcast:31 row_mask:0xc bank_mask:0xf
	s_nop 1
	v_readlane_b32 s16, v60, 63
	s_nop 1
	v_mov_b32_e32 v148, s16
	v_fmamk_f32 v148, v148, 0x3a800000, v66
	v_rsq_f32_e32 v148, v148
	s_nop 0
	s_waitcnt vmcnt(4)
	v_pk_mul_f32 v[68:69], v[68:69], v[148:149] op_sel_hi:[1,0]
	v_pk_mul_f32 v[70:71], v[70:71], v[148:149] op_sel_hi:[1,0]
	v_pk_add_f32 v[116:117], v[116:117], 1.0 op_sel_hi:[1,0]
	v_pk_add_f32 v[118:119], v[118:119], 1.0 op_sel_hi:[1,0]
	v_pk_mul_f32 v[68:69], v[0:1], v[68:69]
	v_pk_mul_f32 v[70:71], v[2:3], v[70:71]
	v_pk_fma_f32 v[68:69], v[68:69], v[116:117], v[132:133]
	v_pk_fma_f32 v[70:71], v[70:71], v[118:119], v[134:135]
	v_cvt_pk_bf16_f32 v68, v68, v69
	v_cvt_pk_bf16_f32 v69, v70, v71
	global_store_dwordx2 v48, v[68:69], s[14:15]
	v_pk_mul_f32 v[72:73], v[72:73], v[148:149] op_sel_hi:[1,0]
	v_pk_mul_f32 v[74:75], v[74:75], v[148:149] op_sel_hi:[1,0]
	v_pk_add_f32 v[120:121], v[120:121], 1.0 op_sel_hi:[1,0]
	v_pk_add_f32 v[122:123], v[122:123], 1.0 op_sel_hi:[1,0]
	v_pk_mul_f32 v[72:73], v[4:5], v[72:73]
	v_pk_mul_f32 v[74:75], v[6:7], v[74:75]
	v_pk_fma_f32 v[72:73], v[72:73], v[120:121], v[136:137]
	v_pk_fma_f32 v[74:75], v[74:75], v[122:123], v[138:139]
	v_cvt_pk_bf16_f32 v72, v72, v73
	v_cvt_pk_bf16_f32 v73, v74, v75
	global_store_dwordx2 v48, v[72:73], s[14:15] offset:512
	v_pk_mul_f32 v[76:77], v[76:77], v[148:149] op_sel_hi:[1,0]
	v_pk_mul_f32 v[78:79], v[78:79], v[148:149] op_sel_hi:[1,0]
	v_pk_add_f32 v[124:125], v[124:125], 1.0 op_sel_hi:[1,0]
	v_pk_add_f32 v[126:127], v[126:127], 1.0 op_sel_hi:[1,0]
	v_pk_mul_f32 v[76:77], v[8:9], v[76:77]
	v_pk_mul_f32 v[78:79], v[10:11], v[78:79]
	v_pk_fma_f32 v[76:77], v[76:77], v[124:125], v[140:141]
	v_pk_fma_f32 v[78:79], v[78:79], v[126:127], v[142:143]
	v_cvt_pk_bf16_f32 v76, v76, v77
	v_cvt_pk_bf16_f32 v77, v78, v79
	global_store_dwordx2 v48, v[76:77], s[14:15] offset:1024
	v_pk_mul_f32 v[80:81], v[80:81], v[148:149] op_sel_hi:[1,0]
	v_pk_mul_f32 v[82:83], v[82:83], v[148:149] op_sel_hi:[1,0]
	v_pk_add_f32 v[128:129], v[128:129], 1.0 op_sel_hi:[1,0]
	v_pk_add_f32 v[130:131], v[130:131], 1.0 op_sel_hi:[1,0]
	v_pk_mul_f32 v[80:81], v[12:13], v[80:81]
	v_pk_mul_f32 v[82:83], v[14:15], v[82:83]
	v_pk_fma_f32 v[80:81], v[80:81], v[128:129], v[144:145]
	v_pk_fma_f32 v[82:83], v[82:83], v[130:131], v[146:147]
	v_cvt_pk_bf16_f32 v80, v80, v81
	v_cvt_pk_bf16_f32 v81, v82, v83
	global_store_dwordx2 v48, v[80:81], s[14:15] offset:1536

.LBB0_196:
	s_lshl_b64 s[6:7], s[6:7], 2
	s_add_u32 s8, s57, s6
	v_lshl_add_u32 v172, s22, 8, v184
	s_addc_u32 s9, s63, s7
	s_lshl_b32 s22, s40, 8
	s_ashr_i32 s23, s22, 31
	s_lshl_b64 s[6:7], s[22:23], 2
	s_add_u32 s6, s8, s6
	s_addc_u32 s7, s9, s7
	s_add_u32 s6, s6, s50
	s_addc_u32 s7, s7, 0
	global_load_dwordx4 v[112:115], v193, s[6:7] offset:16
	global_load_dwordx4 v[116:119], v193, s[6:7]
	global_load_dwordx4 v[104:107], v193, s[6:7] offset:528
	global_load_dwordx4 v[108:111], v193, s[6:7] offset:512
	v_readlane_b32 s6, v254, 6
	v_ashrrev_i32_e32 v173, 31, v172
	v_readlane_b32 s7, v254, 7
	s_cmp_gt_i32 s40, 7
	s_nop 0
	v_lshl_add_u64 v[182:183], v[172:173], 2, s[6:7]
	global_load_dword v152, v[182:183], off
	global_load_dword v208, v[182:183], off offset:64
	global_load_dword v209, v[182:183], off offset:128
	global_load_dword v210, v[182:183], off offset:192
	global_load_dword v211, v[182:183], off offset:512
	global_load_dword v212, v[182:183], off offset:576
	global_load_dword v213, v[182:183], off offset:640
	global_load_dword v214, v[182:183], off offset:704
	v_add_u32_e32 v173, 0x80, v172
	s_waitcnt vmcnt(0)
	v_fmamk_f32 v152, v152, 0x3a800000, v228
	v_rsq_f32_e32 v152, v152
	s_nop 0
	v_pk_fma_f32 v[176:177], v[128:129], v[152:153], v[104:105] op_sel_hi:[1,0,1]
	v_or_b32_e32 v128, 16, v172
	v_ashrrev_i32_e32 v129, 31, v128
	v_pk_fma_f32 v[174:175], v[130:131], v[152:153], v[106:107] op_sel_hi:[1,0,1]
	v_lshl_add_u64 v[130:131], v[128:129], 2, s[6:7]
	s_nop 0
	v_pk_fma_f32 v[178:179], v[134:135], v[152:153], v[110:111] op_sel_hi:[1,0,1]
	v_pk_fma_f32 v[180:181], v[132:133], v[152:153], v[108:109] op_sel_hi:[1,0,1]
	v_pk_fma_f32 v[142:143], v[142:143], v[152:153], v[118:119] op_sel_hi:[1,0,1]
	v_pk_fma_f32 v[140:141], v[140:141], v[152:153], v[116:117] op_sel_hi:[1,0,1]
	v_pk_fma_f32 v[138:139], v[138:139], v[152:153], v[114:115] op_sel_hi:[1,0,1]
	v_pk_fma_f32 v[136:137], v[136:137], v[152:153], v[112:113] op_sel_hi:[1,0,1]
	s_nop 0
	v_fmamk_f32 v129, v208, 0x3a800000, v228
	v_rsq_f32_e32 v130, v129
	v_add_u32_e32 v129, 0x90, v172
	v_pk_fma_f32 v[126:127], v[126:127], v[130:131], v[118:119] op_sel_hi:[1,0,1]
	v_pk_fma_f32 v[124:125], v[124:125], v[130:131], v[116:117] op_sel_hi:[1,0,1]
	v_pk_fma_f32 v[122:123], v[122:123], v[130:131], v[114:115] op_sel_hi:[1,0,1]
	v_pk_fma_f32 v[120:121], v[120:121], v[130:131], v[112:113] op_sel_hi:[1,0,1]
	v_pk_fma_f32 v[132:133], v[102:103], v[130:131], v[110:111] op_sel_hi:[1,0,1]
	v_pk_fma_f32 v[134:135], v[100:101], v[130:131], v[108:109] op_sel_hi:[1,0,1]
	v_pk_fma_f32 v[102:103], v[98:99], v[130:131], v[106:107] op_sel_hi:[1,0,1]
	v_pk_fma_f32 v[130:131], v[96:97], v[130:131], v[104:105] op_sel_hi:[1,0,1]
	v_or_b32_e32 v96, 32, v172
	v_ashrrev_i32_e32 v97, 31, v96
	v_lshl_add_u64 v[98:99], v[96:97], 2, s[6:7]
	s_nop 0
	s_nop 0
	v_fmamk_f32 v97, v209, 0x3a800000, v228
	v_rsq_f32_e32 v152, v97
	v_add_u32_e32 v97, 0xa0, v172
	v_pk_fma_f32 v[98:99], v[86:87], v[152:153], v[110:111] op_sel_hi:[1,0,1]
	v_pk_fma_f32 v[86:87], v[80:81], v[152:153], v[104:105] op_sel_hi:[1,0,1]
	v_or_b32_e32 v80, 48, v172
	v_ashrrev_i32_e32 v81, 31, v80
	v_pk_fma_f32 v[100:101], v[84:85], v[152:153], v[108:109] op_sel_hi:[1,0,1]
	v_pk_fma_f32 v[84:85], v[82:83], v[152:153], v[106:107] op_sel_hi:[1,0,1]
	v_lshl_add_u64 v[82:83], v[80:81], 2, s[6:7]
	s_nop 0
	v_pk_fma_f32 v[94:95], v[94:95], v[152:153], v[118:119] op_sel_hi:[1,0,1]
	v_pk_fma_f32 v[92:93], v[92:93], v[152:153], v[116:117] op_sel_hi:[1,0,1]
	v_pk_fma_f32 v[90:91], v[90:91], v[152:153], v[114:115] op_sel_hi:[1,0,1]
	v_pk_fma_f32 v[88:89], v[88:89], v[152:153], v[112:113] op_sel_hi:[1,0,1]
	s_mov_b64 s[6:7], -1
	s_nop 0
	v_fmamk_f32 v81, v210, 0x3a800000, v228
	v_rsq_f32_e32 v152, v81
	v_add_u32_e32 v81, 0xb0, v172
	v_pk_fma_f32 v[82:83], v[68:69], v[152:153], v[108:109] op_sel_hi:[1,0,1]
	s_nop 0
	v_pk_fma_f32 v[78:79], v[78:79], v[152:153], v[118:119] op_sel_hi:[1,0,1]
	v_pk_fma_f32 v[76:77], v[76:77], v[152:153], v[116:117] op_sel_hi:[1,0,1]
	v_pk_fma_f32 v[74:75], v[74:75], v[152:153], v[114:115] op_sel_hi:[1,0,1]
	v_pk_fma_f32 v[72:73], v[72:73], v[152:153], v[112:113] op_sel_hi:[1,0,1]
	v_pk_fma_f32 v[70:71], v[70:71], v[152:153], v[110:111] op_sel_hi:[1,0,1]
	v_pk_fma_f32 v[66:67], v[66:67], v[152:153], v[106:107] op_sel_hi:[1,0,1]
	v_pk_fma_f32 v[64:65], v[64:65], v[152:153], v[104:105] op_sel_hi:[1,0,1]
	s_nop 0
	v_fmamk_f32 v68, v211, 0x3a800000, v228
	v_rsq_f32_e32 v68, v68
	s_nop 0
	v_pk_fma_f32 v[62:63], v[62:63], v[68:69], v[118:119] op_sel_hi:[1,0,1]
	v_pk_fma_f32 v[60:61], v[60:61], v[68:69], v[116:117] op_sel_hi:[1,0,1]
	v_pk_fma_f32 v[58:59], v[58:59], v[68:69], v[114:115] op_sel_hi:[1,0,1]
	v_pk_fma_f32 v[56:57], v[56:57], v[68:69], v[112:113] op_sel_hi:[1,0,1]
	v_pk_fma_f32 v[54:55], v[54:55], v[68:69], v[110:111] op_sel_hi:[1,0,1]
	v_pk_fma_f32 v[52:53], v[52:53], v[68:69], v[108:109] op_sel_hi:[1,0,1]
	v_pk_fma_f32 v[50:51], v[50:51], v[68:69], v[106:107] op_sel_hi:[1,0,1]
	v_pk_fma_f32 v[48:49], v[48:49], v[68:69], v[104:105] op_sel_hi:[1,0,1]
	s_nop 0
	s_nop 0
	v_fmamk_f32 v68, v212, 0x3a800000, v228
	v_rsq_f32_e32 v68, v68
	s_nop 0
	v_pk_fma_f32 v[46:47], v[46:47], v[68:69], v[118:119] op_sel_hi:[1,0,1]
	v_pk_fma_f32 v[44:45], v[44:45], v[68:69], v[116:117] op_sel_hi:[1,0,1]
	v_pk_fma_f32 v[42:43], v[42:43], v[68:69], v[114:115] op_sel_hi:[1,0,1]
	v_pk_fma_f32 v[40:41], v[40:41], v[68:69], v[112:113] op_sel_hi:[1,0,1]
	v_pk_fma_f32 v[38:39], v[38:39], v[68:69], v[110:111] op_sel_hi:[1,0,1]
	v_pk_fma_f32 v[36:37], v[36:37], v[68:69], v[108:109] op_sel_hi:[1,0,1]
	v_pk_fma_f32 v[34:35], v[34:35], v[68:69], v[106:107] op_sel_hi:[1,0,1]
	v_pk_fma_f32 v[32:33], v[32:33], v[68:69], v[104:105] op_sel_hi:[1,0,1]
	s_nop 0
	s_nop 0
	v_fmamk_f32 v68, v213, 0x3a800000, v228
	v_rsq_f32_e32 v68, v68
	s_nop 0
	v_pk_fma_f32 v[30:31], v[30:31], v[68:69], v[118:119] op_sel_hi:[1,0,1]
	v_pk_fma_f32 v[28:29], v[28:29], v[68:69], v[116:117] op_sel_hi:[1,0,1]
	v_pk_fma_f32 v[26:27], v[26:27], v[68:69], v[114:115] op_sel_hi:[1,0,1]
	v_pk_fma_f32 v[24:25], v[24:25], v[68:69], v[112:113] op_sel_hi:[1,0,1]
	v_pk_fma_f32 v[22:23], v[22:23], v[68:69], v[110:111] op_sel_hi:[1,0,1]
	v_pk_fma_f32 v[20:21], v[20:21], v[68:69], v[108:109] op_sel_hi:[1,0,1]
	v_pk_fma_f32 v[18:19], v[18:19], v[68:69], v[106:107] op_sel_hi:[1,0,1]
	v_pk_fma_f32 v[16:17], v[16:17], v[68:69], v[104:105] op_sel_hi:[1,0,1]
	s_nop 0
	s_nop 0
	v_fmamk_f32 v68, v214, 0x3a800000, v228
	v_rsq_f32_e32 v68, v68
	s_nop 0
	v_pk_fma_f32 v[14:15], v[14:15], v[68:69], v[118:119] op_sel_hi:[1,0,1]
	v_pk_fma_f32 v[12:13], v[12:13], v[68:69], v[116:117] op_sel_hi:[1,0,1]
	v_pk_fma_f32 v[10:11], v[10:11], v[68:69], v[114:115] op_sel_hi:[1,0,1]
	v_pk_fma_f32 v[8:9], v[8:9], v[68:69], v[112:113] op_sel_hi:[1,0,1]
	v_pk_fma_f32 v[6:7], v[6:7], v[68:69], v[110:111] op_sel_hi:[1,0,1]
	v_pk_fma_f32 v[4:5], v[4:5], v[68:69], v[108:109] op_sel_hi:[1,0,1]
	v_pk_fma_f32 v[2:3], v[2:3], v[68:69], v[106:107] op_sel_hi:[1,0,1]
	v_pk_fma_f32 v[0:1], v[0:1], v[68:69], v[104:105] op_sel_hi:[1,0,1]
	s_cbranch_scc1 .LBB0_199
	s_andn2_b64 vcc, exec, s[6:7]
	s_cbranch_vccz .LBB0_204

.LBB0_789:
	s_or_b64 exec, exec, s[2:3]
	v_readlane_b32 s0, v254, 9
	s_waitcnt lgkmcnt(0)
	v_and_b32_e32 v124, 64, v230
	v_add_u32_e32 v190, 64, v124
	v_or_b32_e32 v64, s0, v241
	v_lshlrev_b32_e32 v64, 2, v64
	global_load_dword v131, v64, s[4:5]
	v_xor_b32_e32 v124, 1, v230
	v_cmp_lt_i32_e32 vcc, v124, v190
	v_lshlrev_b32_e32 v152, 1, v241
	s_movk_i32 s2, 0x100
	v_cndmask_b32_e32 v124, v230, v124, vcc
	v_lshlrev_b32_e32 v202, 2, v124
	v_xor_b32_e32 v124, 2, v230
	v_cmp_lt_i32_e32 vcc, v124, v190
	s_mov_b64 s[0:1], 0
	global_load_dword v130, v64, s[4:5] offset:128
	v_cndmask_b32_e32 v124, v230, v124, vcc
	v_lshlrev_b32_e32 v203, 2, v124
	v_xor_b32_e32 v124, 4, v230
	v_cmp_lt_i32_e32 vcc, v124, v190
	global_load_dword v129, v64, s[4:5] offset:256
	v_cndmask_b32_e32 v124, v230, v124, vcc
	global_load_dword v128, v64, s[4:5] offset:384
	v_lshlrev_b32_e32 v204, 2, v124
	v_xor_b32_e32 v124, 8, v230
	v_cmp_lt_i32_e32 vcc, v124, v190
	v_cndmask_b32_e32 v124, v230, v124, vcc
	global_load_dwordx4 v[132:135], v[144:145], off
	global_load_dwordx4 v[120:123], v[144:145], off offset:1024
	global_load_dwordx4 v[116:119], v[144:145], off offset:2048
	global_load_dwordx4 v[112:115], v[144:145], off offset:3072
	s_mov_b64 s[100:101], 0x2000
	v_lshl_add_u64 v[146:147], v[144:145], 0, s[100:101]
	s_mov_b64 s[100:101], 0x3000
	v_lshl_add_u64 v[148:149], v[144:145], 0, s[100:101]
	global_load_dwordx4 v[108:111], v[146:147], off offset:-4096
	global_load_dwordx4 v[104:107], v[146:147], off offset:-3072
	global_load_dwordx4 v[100:103], v[146:147], off offset:-2048
	global_load_dwordx4 v[96:99], v[146:147], off offset:-1024
	global_load_dwordx4 v[92:95], v[146:147], off
	global_load_dwordx4 v[88:91], v[146:147], off offset:1024
	global_load_dwordx4 v[84:87], v[146:147], off offset:2048
	global_load_dwordx4 v[80:83], v[146:147], off offset:3072
	global_load_dwordx4 v[76:79], v[148:149], off
	global_load_dwordx4 v[72:75], v[148:149], off offset:1024
	global_load_dwordx4 v[68:71], v[148:149], off offset:2048
	global_load_dwordx4 v[64:67], v[148:149], off offset:3072
	ds_read_b64 v[126:127], v240 offset:49152
	v_lshlrev_b32_e32 v205, 2, v124
	v_xor_b32_e32 v124, 16, v230
	v_cmp_lt_i32_e32 vcc, v124, v190
	s_waitcnt lgkmcnt(0)
	v_rcp_f32_e32 v126, v126
	v_cndmask_b32_e32 v124, v230, v124, vcc
	v_lshlrev_b32_e32 v206, 2, v124
	v_lshlrev_b32_e32 v124, 5, v243
	v_mul_f32_e32 v126, s20, v126
	v_ashrrev_i32_e32 v125, 31, v124
	v_lshl_add_u64 v[124:125], v[124:125], 0, s[8:9]
	v_lshl_or_b32 v124, v242, 2, v124
	s_and_b64 vcc, exec, s[6:7]
	s_waitcnt vmcnt(15)
	v_mul_f32_e32 v131, v239, v131
	v_mul_f32_e32 v130, v239, v130
	v_mul_f32_e32 v129, v239, v129
	v_mul_f32_e32 v128, v239, v128
	v_fma_f32 v32, -v32, v126, v133
	v_fma_f32 v48, -v48, v126, v132
	v_mul_f32_e32 v132, v32, v32
	v_fmac_f32_e32 v132, v48, v48
	v_fma_f32 v16, -v16, v126, v134
	v_fmac_f32_e32 v132, v16, v16
	v_fma_f32 v0, -v0, v126, v135
	v_fmac_f32_e32 v132, v0, v0
	ds_bpermute_b32 v126, v202, v132
	s_waitcnt lgkmcnt(0)
	v_add_f32_e32 v126, v132, v126
	ds_bpermute_b32 v132, v203, v126
	s_waitcnt lgkmcnt(0)
	v_add_f32_e32 v126, v126, v132
	ds_bpermute_b32 v132, v204, v126
	s_waitcnt lgkmcnt(0)
	v_add_f32_e32 v126, v126, v132
	ds_bpermute_b32 v132, v205, v126
	s_waitcnt lgkmcnt(0)
	v_add_f32_e32 v126, v126, v132
	ds_bpermute_b32 v132, v206, v126
	s_waitcnt lgkmcnt(0)
	v_add_f32_e32 v126, v126, v132
	v_fmamk_f32 v126, v126, 0x3c000000, v228
	v_rsq_f32_e32 v126, v126
	v_lshlrev_b64 v[132:133], 11, v[124:125]
	v_lshl_add_u64 v[132:133], s[42:43], 0, v[132:133]
	v_lshl_add_u64 v[132:133], v[132:133], 0, v[152:153]
	v_mul_f32_e32 v48, v48, v126
	v_mul_f32_e32 v48, v131, v48
	v_bfe_u32 v134, v48, 16, 1
	v_mul_f32_e32 v32, v32, v126
	v_add3_u32 v48, v48, v134, s96
	v_mul_f32_e32 v32, v130, v32
	global_store_short_d16_hi v[132:133], v48, off offset:512
	v_bfe_u32 v48, v32, 16, 1
	v_mul_f32_e32 v16, v16, v126
	v_add3_u32 v32, v32, v48, s96
	v_mul_f32_e32 v16, v129, v16
	global_store_short_d16_hi v[132:133], v32, off offset:576
	v_bfe_u32 v32, v16, 16, 1
	v_mul_f32_e32 v0, v0, v126
	v_add3_u32 v16, v16, v32, s96
	v_mul_f32_e32 v0, v128, v0
	global_store_short_d16_hi v[132:133], v16, off offset:640
	v_bfe_u32 v16, v0, 16, 1
	v_add3_u32 v0, v0, v16, s96
	global_store_short_d16_hi v[132:133], v0, off offset:704
	v_rcp_f32_e32 v0, v127
	s_nop 0
	v_mul_f32_e32 v0, s20, v0
	s_waitcnt vmcnt(18)
	v_fma_f32 v32, -v33, v0, v121
	v_fma_f32 v48, -v49, v0, v120
	v_mul_f32_e32 v33, v32, v32
	v_fmac_f32_e32 v33, v48, v48
	v_fma_f32 v17, -v17, v0, v122
	v_fmac_f32_e32 v33, v17, v17
	v_fma_f32 v16, -v1, v0, v123
	v_fmac_f32_e32 v33, v16, v16
	ds_bpermute_b32 v0, v202, v33
	s_waitcnt lgkmcnt(0)
	v_add_f32_e32 v0, v33, v0
	ds_bpermute_b32 v1, v203, v0
	s_waitcnt lgkmcnt(0)
	v_add_f32_e32 v0, v0, v1
	ds_bpermute_b32 v1, v204, v0
	s_waitcnt lgkmcnt(0)
	v_add_f32_e32 v0, v0, v1
	ds_bpermute_b32 v1, v205, v0
	s_waitcnt lgkmcnt(0)
	v_add_f32_e32 v0, v0, v1
	ds_bpermute_b32 v1, v206, v0
	s_waitcnt lgkmcnt(0)
	v_add_f32_e32 v0, v0, v1
	v_fmamk_f32 v0, v0, 0x3c000000, v228
	v_rsq_f32_e32 v33, v0
	v_or_b32_e32 v0, 1, v124
	v_mov_b32_e32 v1, v125
	v_lshlrev_b64 v[0:1], 11, v[0:1]
	v_mul_f32_e32 v48, v48, v33
	v_mul_f32_e32 v48, v131, v48
	v_lshl_add_u64 v[0:1], s[42:43], 0, v[0:1]
	v_bfe_u32 v49, v48, 16, 1
	v_mul_f32_e32 v32, v32, v33
	v_lshl_add_u64 v[0:1], v[0:1], 0, v[152:153]
	v_add3_u32 v48, v48, v49, s96
	v_mul_f32_e32 v32, v130, v32
	global_store_short_d16_hi v[0:1], v48, off offset:512
	v_bfe_u32 v48, v32, 16, 1
	v_mul_f32_e32 v17, v17, v33
	v_add3_u32 v32, v32, v48, s96
	v_mul_f32_e32 v17, v129, v17
	global_store_short_d16_hi v[0:1], v32, off offset:576
	v_bfe_u32 v32, v17, 16, 1
	v_mul_f32_e32 v16, v16, v33
	v_add3_u32 v17, v17, v32, s96
	v_mul_f32_e32 v16, v128, v16
	global_store_short_d16_hi v[0:1], v17, off offset:640
	v_bfe_u32 v17, v16, 16, 1
	v_add3_u32 v16, v16, v17, s96
	global_store_short_d16_hi v[0:1], v16, off offset:704
	ds_read_b64 v[0:1], v240 offset:49160
	v_mov_b32_e32 v17, v125
	s_waitcnt lgkmcnt(0)
	v_rcp_f32_e32 v0, v0
	s_nop 0
	v_mul_f32_e32 v0, s20, v0
	s_waitcnt vmcnt(21)
	v_fma_f32 v33, -v34, v0, v117
	v_fma_f32 v32, -v50, v0, v116
	v_mul_f32_e32 v16, v33, v33
	v_fmac_f32_e32 v16, v32, v32
	v_fma_f32 v18, -v18, v0, v118
	v_fmac_f32_e32 v16, v18, v18
	v_fma_f32 v0, -v2, v0, v119
	v_fmac_f32_e32 v16, v0, v0
	ds_bpermute_b32 v2, v202, v16
	s_waitcnt lgkmcnt(0)
	v_add_f32_e32 v2, v16, v2
	ds_bpermute_b32 v16, v203, v2
	s_waitcnt lgkmcnt(0)
	v_add_f32_e32 v2, v2, v16
	ds_bpermute_b32 v16, v204, v2
	s_waitcnt lgkmcnt(0)
	v_add_f32_e32 v2, v2, v16
	ds_bpermute_b32 v16, v205, v2
	s_waitcnt lgkmcnt(0)
	v_add_f32_e32 v2, v2, v16
	ds_bpermute_b32 v16, v206, v2
	s_waitcnt lgkmcnt(0)
	v_add_f32_e32 v2, v2, v16
	v_fmamk_f32 v2, v2, 0x3c000000, v228
	v_rsq_f32_e32 v2, v2
	v_or_b32_e32 v16, 2, v124
	v_lshlrev_b64 v[16:17], 11, v[16:17]
	v_lshl_add_u64 v[16:17], s[42:43], 0, v[16:17]
	v_mul_f32_e32 v32, v32, v2
	v_mul_f32_e32 v32, v131, v32
	v_bfe_u32 v34, v32, 16, 1
	v_mul_f32_e32 v0, v0, v2
	v_lshl_add_u64 v[16:17], v[16:17], 0, v[152:153]
	v_add3_u32 v32, v32, v34, s96
	v_mul_f32_e32 v0, v128, v0
	global_store_short_d16_hi v[16:17], v32, off offset:512
	v_mul_f32_e32 v32, v33, v2
	v_mul_f32_e32 v18, v18, v2
	v_bfe_u32 v2, v0, 16, 1
	v_add3_u32 v0, v0, v2, s96
	v_mul_f32_e32 v32, v130, v32
	global_store_short_d16_hi v[16:17], v0, off offset:704
	v_rcp_f32_e32 v0, v1
	v_bfe_u32 v33, v32, 16, 1
	v_add3_u32 v32, v32, v33, s96
	v_mul_f32_e32 v18, v129, v18
	global_store_short_d16_hi v[16:17], v32, off offset:576
	v_bfe_u32 v32, v18, 16, 1
	v_add3_u32 v18, v18, v32, s96
	v_mul_f32_e32 v0, s20, v0
	global_store_short_d16_hi v[16:17], v18, off offset:640
	s_waitcnt vmcnt(24)
	v_fma_f32 v16, -v35, v0, v113
	v_fma_f32 v2, -v51, v0, v112
	v_mul_f32_e32 v1, v16, v16
	v_fmac_f32_e32 v1, v2, v2
	v_fma_f32 v17, -v19, v0, v114
	v_fmac_f32_e32 v1, v17, v17
	v_fma_f32 v3, -v3, v0, v115
	v_fmac_f32_e32 v1, v3, v3
	ds_bpermute_b32 v0, v202, v1
	s_waitcnt lgkmcnt(0)
	v_add_f32_e32 v0, v1, v0
	ds_bpermute_b32 v1, v203, v0
	s_waitcnt lgkmcnt(0)
	v_add_f32_e32 v0, v0, v1
	ds_bpermute_b32 v1, v204, v0
	s_waitcnt lgkmcnt(0)
	v_add_f32_e32 v0, v0, v1
	ds_bpermute_b32 v1, v205, v0
	s_waitcnt lgkmcnt(0)
	v_add_f32_e32 v0, v0, v1
	ds_bpermute_b32 v1, v206, v0
	s_waitcnt lgkmcnt(0)
	v_add_f32_e32 v0, v0, v1
	v_fmamk_f32 v0, v0, 0x3c000000, v228
	v_rsq_f32_e32 v18, v0
	v_or_b32_e32 v0, 3, v124
	v_mov_b32_e32 v1, v125
	v_lshlrev_b64 v[0:1], 11, v[0:1]
	v_mul_f32_e32 v2, v2, v18
	v_mul_f32_e32 v2, v131, v2
	v_lshl_add_u64 v[0:1], s[42:43], 0, v[0:1]
	v_bfe_u32 v19, v2, 16, 1
	v_lshl_add_u64 v[0:1], v[0:1], 0, v[152:153]
	v_add3_u32 v2, v2, v19, s96
	global_store_short_d16_hi v[0:1], v2, off offset:512
	v_mul_f32_e32 v2, v16, v18
	v_mul_f32_e32 v2, v130, v2
	v_bfe_u32 v16, v2, 16, 1
	v_add3_u32 v2, v2, v16, s96
	global_store_short_d16_hi v[0:1], v2, off offset:576
	v_mul_f32_e32 v2, v17, v18
	v_mul_f32_e32 v2, v129, v2
	v_bfe_u32 v16, v2, 16, 1
	v_add3_u32 v2, v2, v16, s96
	global_store_short_d16_hi v[0:1], v2, off offset:640
	v_mul_f32_e32 v2, v3, v18
	v_mul_f32_e32 v2, v128, v2
	v_bfe_u32 v3, v2, 16, 1
	v_add3_u32 v2, v2, v3, s96
	global_store_short_d16_hi v[0:1], v2, off offset:704
	ds_read_b64 v[0:1], v240 offset:49184
	s_waitcnt lgkmcnt(0)
	v_rcp_f32_e32 v0, v0
	s_nop 0
	v_mul_f32_e32 v0, s20, v0
	s_waitcnt vmcnt(27)
	v_fma_f32 v17, -v36, v0, v109
	v_fma_f32 v16, -v52, v0, v108
	v_mul_f32_e32 v2, v17, v17
	v_fmac_f32_e32 v2, v16, v16
	v_fma_f32 v18, -v20, v0, v110
	v_fmac_f32_e32 v2, v18, v18
	v_fma_f32 v0, -v4, v0, v111
	v_fmac_f32_e32 v2, v0, v0
	ds_bpermute_b32 v3, v202, v2
	s_waitcnt lgkmcnt(0)
	v_add_f32_e32 v2, v2, v3
	ds_bpermute_b32 v3, v203, v2
	s_waitcnt lgkmcnt(0)
	v_add_f32_e32 v2, v2, v3
	ds_bpermute_b32 v3, v204, v2
	s_waitcnt lgkmcnt(0)
	v_add_f32_e32 v2, v2, v3
	ds_bpermute_b32 v3, v205, v2
	s_waitcnt lgkmcnt(0)
	v_add_f32_e32 v2, v2, v3
	ds_bpermute_b32 v3, v206, v2
	s_waitcnt lgkmcnt(0)
	v_add_f32_e32 v2, v2, v3
	v_fmamk_f32 v2, v2, 0x3c000000, v228
	v_rsq_f32_e32 v4, v2
	v_or_b32_e32 v2, 8, v124
	v_mov_b32_e32 v3, v125
	v_lshlrev_b64 v[2:3], 11, v[2:3]
	v_mul_f32_e32 v16, v16, v4
	v_mul_f32_e32 v16, v131, v16
	v_lshl_add_u64 v[2:3], s[42:43], 0, v[2:3]
	v_bfe_u32 v19, v16, 16, 1
	v_lshl_add_u64 v[2:3], v[2:3], 0, v[152:153]
	v_add3_u32 v16, v16, v19, s96
	global_store_short_d16_hi v[2:3], v16, off offset:512
	v_mul_f32_e32 v16, v17, v4
	v_mul_f32_e32 v16, v130, v16
	v_bfe_u32 v17, v16, 16, 1
	v_mul_f32_e32 v0, v0, v4
	v_add3_u32 v16, v16, v17, s96
	v_mul_f32_e32 v0, v128, v0
	global_store_short_d16_hi v[2:3], v16, off offset:576
	v_mul_f32_e32 v16, v18, v4
	v_bfe_u32 v4, v0, 16, 1
	v_add3_u32 v0, v0, v4, s96
	global_store_short_d16_hi v[2:3], v0, off offset:704
	v_rcp_f32_e32 v0, v1
	v_mul_f32_e32 v16, v129, v16
	v_bfe_u32 v17, v16, 16, 1
	v_add3_u32 v16, v16, v17, s96
	v_mul_f32_e32 v0, s20, v0
	global_store_short_d16_hi v[2:3], v16, off offset:640
	s_waitcnt vmcnt(30)
	v_fma_f32 v3, -v37, v0, v105
	v_fma_f32 v2, -v53, v0, v104
	v_mul_f32_e32 v1, v3, v3
	v_fmac_f32_e32 v1, v2, v2
	v_fma_f32 v4, -v21, v0, v106
	v_fmac_f32_e32 v1, v4, v4
	v_fma_f32 v5, -v5, v0, v107
	v_fmac_f32_e32 v1, v5, v5
	ds_bpermute_b32 v0, v202, v1
	s_waitcnt lgkmcnt(0)
	v_add_f32_e32 v0, v1, v0
	ds_bpermute_b32 v1, v203, v0
	s_waitcnt lgkmcnt(0)
	v_add_f32_e32 v0, v0, v1
	ds_bpermute_b32 v1, v204, v0
	s_waitcnt lgkmcnt(0)
	v_add_f32_e32 v0, v0, v1
	ds_bpermute_b32 v1, v205, v0
	s_waitcnt lgkmcnt(0)
	v_add_f32_e32 v0, v0, v1
	ds_bpermute_b32 v1, v206, v0
	s_waitcnt lgkmcnt(0)
	v_add_f32_e32 v0, v0, v1
	v_fmamk_f32 v0, v0, 0x3c000000, v228
	v_rsq_f32_e32 v16, v0
	v_or_b32_e32 v0, 9, v124
	v_mov_b32_e32 v1, v125
	v_lshlrev_b64 v[0:1], 11, v[0:1]
	v_mul_f32_e32 v2, v2, v16
	v_mul_f32_e32 v2, v131, v2
	v_lshl_add_u64 v[0:1], s[42:43], 0, v[0:1]
	v_bfe_u32 v17, v2, 16, 1
	v_lshl_add_u64 v[0:1], v[0:1], 0, v[152:153]
	v_add3_u32 v2, v2, v17, s96
	global_store_short_d16_hi v[0:1], v2, off offset:512
	v_mul_f32_e32 v2, v3, v16
	v_mul_f32_e32 v2, v130, v2
	v_bfe_u32 v3, v2, 16, 1
	v_add3_u32 v2, v2, v3, s96
	global_store_short_d16_hi v[0:1], v2, off offset:576
	v_mul_f32_e32 v2, v4, v16
	v_mul_f32_e32 v2, v129, v2
	v_bfe_u32 v3, v2, 16, 1
	v_add3_u32 v2, v2, v3, s96
	global_store_short_d16_hi v[0:1], v2, off offset:640
	v_mul_f32_e32 v2, v5, v16
	v_mul_f32_e32 v2, v128, v2
	v_bfe_u32 v3, v2, 16, 1
	v_add3_u32 v2, v2, v3, s96
	global_store_short_d16_hi v[0:1], v2, off offset:704
	ds_read_b64 v[0:1], v240 offset:49192
	s_waitcnt lgkmcnt(0)
	v_rcp_f32_e32 v0, v0
	s_nop 0
	v_mul_f32_e32 v0, s20, v0
	s_waitcnt vmcnt(33)
	v_fma_f32 v5, -v38, v0, v101
	v_fma_f32 v4, -v54, v0, v100
	v_mul_f32_e32 v2, v5, v5
	v_fmac_f32_e32 v2, v4, v4
	v_fma_f32 v16, -v22, v0, v102
	v_fmac_f32_e32 v2, v16, v16
	v_fma_f32 v0, -v6, v0, v103
	v_fmac_f32_e32 v2, v0, v0
	ds_bpermute_b32 v3, v202, v2
	s_waitcnt lgkmcnt(0)
	v_add_f32_e32 v2, v2, v3
	ds_bpermute_b32 v3, v203, v2
	s_waitcnt lgkmcnt(0)
	v_add_f32_e32 v2, v2, v3
	ds_bpermute_b32 v3, v204, v2
	s_waitcnt lgkmcnt(0)
	v_add_f32_e32 v2, v2, v3
	ds_bpermute_b32 v3, v205, v2
	s_waitcnt lgkmcnt(0)
	v_add_f32_e32 v2, v2, v3
	ds_bpermute_b32 v3, v206, v2
	s_waitcnt lgkmcnt(0)
	v_add_f32_e32 v2, v2, v3
	v_fmamk_f32 v2, v2, 0x3c000000, v228
	v_rsq_f32_e32 v6, v2
	v_or_b32_e32 v2, 10, v124
	v_mov_b32_e32 v3, v125
	v_lshlrev_b64 v[2:3], 11, v[2:3]
	v_mul_f32_e32 v4, v4, v6
	v_mul_f32_e32 v4, v131, v4
	v_lshl_add_u64 v[2:3], s[42:43], 0, v[2:3]
	v_bfe_u32 v17, v4, 16, 1
	v_lshl_add_u64 v[2:3], v[2:3], 0, v[152:153]
	v_add3_u32 v4, v4, v17, s96
	global_store_short_d16_hi v[2:3], v4, off offset:512
	v_mul_f32_e32 v4, v5, v6
	v_mul_f32_e32 v4, v130, v4
	v_bfe_u32 v5, v4, 16, 1
	v_add3_u32 v4, v4, v5, s96
	global_store_short_d16_hi v[2:3], v4, off offset:576
	v_mul_f32_e32 v4, v16, v6
	v_mul_f32_e32 v4, v129, v4
	v_bfe_u32 v5, v4, 16, 1
	v_mul_f32_e32 v0, v0, v6
	v_add3_u32 v4, v4, v5, s96
	v_mul_f32_e32 v0, v128, v0
	global_store_short_d16_hi v[2:3], v4, off offset:640
	v_bfe_u32 v4, v0, 16, 1
	v_add3_u32 v0, v0, v4, s96
	global_store_short_d16_hi v[2:3], v0, off offset:704
	v_rcp_f32_e32 v0, v1
	s_nop 0
	v_mul_f32_e32 v0, s20, v0
	s_waitcnt vmcnt(36)
	v_fma_f32 v3, -v39, v0, v97
	v_fma_f32 v2, -v55, v0, v96
	v_mul_f32_e32 v1, v3, v3
	v_fmac_f32_e32 v1, v2, v2
	v_fma_f32 v4, -v23, v0, v98
	v_fmac_f32_e32 v1, v4, v4
	v_fma_f32 v5, -v7, v0, v99
	v_fmac_f32_e32 v1, v5, v5
	ds_bpermute_b32 v0, v202, v1
	s_waitcnt lgkmcnt(0)
	v_add_f32_e32 v0, v1, v0
	ds_bpermute_b32 v1, v203, v0
	s_waitcnt lgkmcnt(0)
	v_add_f32_e32 v0, v0, v1
	ds_bpermute_b32 v1, v204, v0
	s_waitcnt lgkmcnt(0)
	v_add_f32_e32 v0, v0, v1
	ds_bpermute_b32 v1, v205, v0
	s_waitcnt lgkmcnt(0)
	v_add_f32_e32 v0, v0, v1
	ds_bpermute_b32 v1, v206, v0
	s_waitcnt lgkmcnt(0)
	v_add_f32_e32 v0, v0, v1
	v_fmamk_f32 v0, v0, 0x3c000000, v228
	v_rsq_f32_e32 v6, v0
	v_or_b32_e32 v0, 11, v124
	v_mov_b32_e32 v1, v125
	v_lshlrev_b64 v[0:1], 11, v[0:1]
	v_mul_f32_e32 v2, v2, v6
	v_mul_f32_e32 v2, v131, v2
	v_lshl_add_u64 v[0:1], s[42:43], 0, v[0:1]
	v_bfe_u32 v7, v2, 16, 1
	v_lshl_add_u64 v[0:1], v[0:1], 0, v[152:153]
	v_add3_u32 v2, v2, v7, s96
	global_store_short_d16_hi v[0:1], v2, off offset:512
	v_mul_f32_e32 v2, v3, v6
	v_mul_f32_e32 v2, v130, v2
	v_bfe_u32 v3, v2, 16, 1
	v_add3_u32 v2, v2, v3, s96
	global_store_short_d16_hi v[0:1], v2, off offset:576
	v_mul_f32_e32 v2, v4, v6
	v_mul_f32_e32 v2, v129, v2
	v_bfe_u32 v3, v2, 16, 1
	v_add3_u32 v2, v2, v3, s96
	global_store_short_d16_hi v[0:1], v2, off offset:640
	v_mul_f32_e32 v2, v5, v6
	v_mul_f32_e32 v2, v128, v2
	v_bfe_u32 v3, v2, 16, 1
	v_add3_u32 v2, v2, v3, s96
	global_store_short_d16_hi v[0:1], v2, off offset:704
	ds_read_b64 v[0:1], v240 offset:49216
	s_waitcnt lgkmcnt(0)
	v_rcp_f32_e32 v0, v0
	s_nop 0
	v_mul_f32_e32 v0, s20, v0
	s_waitcnt vmcnt(39)
	v_fma_f32 v5, -v40, v0, v93
	v_fma_f32 v4, -v56, v0, v92
	v_mul_f32_e32 v2, v5, v5
	v_fmac_f32_e32 v2, v4, v4
	v_fma_f32 v6, -v24, v0, v94
	v_fmac_f32_e32 v2, v6, v6
	v_fma_f32 v0, -v8, v0, v95
	v_fmac_f32_e32 v2, v0, v0
	ds_bpermute_b32 v3, v202, v2
	s_waitcnt lgkmcnt(0)
	v_add_f32_e32 v2, v2, v3
	ds_bpermute_b32 v3, v203, v2
	s_waitcnt lgkmcnt(0)
	v_add_f32_e32 v2, v2, v3
	ds_bpermute_b32 v3, v204, v2
	s_waitcnt lgkmcnt(0)
	v_add_f32_e32 v2, v2, v3
	ds_bpermute_b32 v3, v205, v2
	s_waitcnt lgkmcnt(0)
	v_add_f32_e32 v2, v2, v3
	ds_bpermute_b32 v3, v206, v2
	s_waitcnt lgkmcnt(0)
	v_add_f32_e32 v2, v2, v3
	v_fmamk_f32 v2, v2, 0x3c000000, v228
	v_rsq_f32_e32 v7, v2
	v_or_b32_e32 v2, 16, v124
	v_mov_b32_e32 v3, v125
	v_lshlrev_b64 v[2:3], 11, v[2:3]
	v_mul_f32_e32 v4, v4, v7
	v_mul_f32_e32 v4, v131, v4
	v_lshl_add_u64 v[2:3], s[42:43], 0, v[2:3]
	v_bfe_u32 v8, v4, 16, 1
	v_lshl_add_u64 v[2:3], v[2:3], 0, v[152:153]
	v_add3_u32 v4, v4, v8, s96
	global_store_short_d16_hi v[2:3], v4, off offset:512
	v_mul_f32_e32 v4, v5, v7
	v_mul_f32_e32 v4, v130, v4
	v_bfe_u32 v5, v4, 16, 1
	v_add3_u32 v4, v4, v5, s96
	global_store_short_d16_hi v[2:3], v4, off offset:576
	v_mul_f32_e32 v4, v6, v7
	v_mul_f32_e32 v4, v129, v4
	v_bfe_u32 v5, v4, 16, 1
	v_mul_f32_e32 v0, v0, v7
	v_add3_u32 v4, v4, v5, s96
	v_mul_f32_e32 v0, v128, v0
	global_store_short_d16_hi v[2:3], v4, off offset:640
	v_bfe_u32 v4, v0, 16, 1
	v_add3_u32 v0, v0, v4, s96
	global_store_short_d16_hi v[2:3], v0, off offset:704
	v_rcp_f32_e32 v0, v1
	s_nop 0
	v_mul_f32_e32 v0, s20, v0
	s_waitcnt vmcnt(42)
	v_fma_f32 v3, -v41, v0, v89
	v_fma_f32 v2, -v57, v0, v88
	v_mul_f32_e32 v1, v3, v3
	v_fmac_f32_e32 v1, v2, v2
	v_fma_f32 v4, -v25, v0, v90
	v_fmac_f32_e32 v1, v4, v4
	v_fma_f32 v5, -v9, v0, v91
	v_fmac_f32_e32 v1, v5, v5
	ds_bpermute_b32 v0, v202, v1
	s_waitcnt lgkmcnt(0)
	v_add_f32_e32 v0, v1, v0
	ds_bpermute_b32 v1, v203, v0
	s_waitcnt lgkmcnt(0)
	v_add_f32_e32 v0, v0, v1
	ds_bpermute_b32 v1, v204, v0
	s_waitcnt lgkmcnt(0)
	v_add_f32_e32 v0, v0, v1
	ds_bpermute_b32 v1, v205, v0
	s_waitcnt lgkmcnt(0)
	v_add_f32_e32 v0, v0, v1
	ds_bpermute_b32 v1, v206, v0
	s_waitcnt lgkmcnt(0)
	v_add_f32_e32 v0, v0, v1
	v_fmamk_f32 v0, v0, 0x3c000000, v228
	v_rsq_f32_e32 v6, v0
	v_or_b32_e32 v0, 17, v124
	v_mov_b32_e32 v1, v125
	v_lshlrev_b64 v[0:1], 11, v[0:1]
	v_mul_f32_e32 v2, v2, v6
	v_mul_f32_e32 v2, v131, v2
	v_lshl_add_u64 v[0:1], s[42:43], 0, v[0:1]
	v_bfe_u32 v7, v2, 16, 1
	v_lshl_add_u64 v[0:1], v[0:1], 0, v[152:153]
	v_add3_u32 v2, v2, v7, s96
	global_store_short_d16_hi v[0:1], v2, off offset:512
	v_mul_f32_e32 v2, v3, v6
	v_mul_f32_e32 v2, v130, v2
	v_bfe_u32 v3, v2, 16, 1
	v_add3_u32 v2, v2, v3, s96
	global_store_short_d16_hi v[0:1], v2, off offset:576
	v_mul_f32_e32 v2, v4, v6
	v_mul_f32_e32 v2, v129, v2
	v_bfe_u32 v3, v2, 16, 1
	v_add3_u32 v2, v2, v3, s96
	global_store_short_d16_hi v[0:1], v2, off offset:640
	v_mul_f32_e32 v2, v5, v6
	v_mul_f32_e32 v2, v128, v2
	v_bfe_u32 v3, v2, 16, 1
	v_add3_u32 v2, v2, v3, s96
	global_store_short_d16_hi v[0:1], v2, off offset:704
	ds_read_b64 v[0:1], v240 offset:49224
	s_waitcnt lgkmcnt(0)
	v_rcp_f32_e32 v0, v0
	s_nop 0
	v_mul_f32_e32 v0, s20, v0
	s_waitcnt vmcnt(45)
	v_fma_f32 v5, -v42, v0, v85
	v_fma_f32 v4, -v58, v0, v84
	v_mul_f32_e32 v2, v5, v5
	v_fmac_f32_e32 v2, v4, v4
	v_fma_f32 v6, -v26, v0, v86
	v_fmac_f32_e32 v2, v6, v6
	v_fma_f32 v0, -v10, v0, v87
	v_fmac_f32_e32 v2, v0, v0
	ds_bpermute_b32 v3, v202, v2
	s_waitcnt lgkmcnt(0)
	v_add_f32_e32 v2, v2, v3
	ds_bpermute_b32 v3, v203, v2
	s_waitcnt lgkmcnt(0)
	v_add_f32_e32 v2, v2, v3
	ds_bpermute_b32 v3, v204, v2
	s_waitcnt lgkmcnt(0)
	v_add_f32_e32 v2, v2, v3
	ds_bpermute_b32 v3, v205, v2
	s_waitcnt lgkmcnt(0)
	v_add_f32_e32 v2, v2, v3
	ds_bpermute_b32 v3, v206, v2
	s_waitcnt lgkmcnt(0)
	v_add_f32_e32 v2, v2, v3
	v_fmamk_f32 v2, v2, 0x3c000000, v228
	v_rsq_f32_e32 v7, v2
	v_or_b32_e32 v2, 18, v124
	v_mov_b32_e32 v3, v125
	v_lshlrev_b64 v[2:3], 11, v[2:3]
	v_mul_f32_e32 v4, v4, v7
	v_mul_f32_e32 v4, v131, v4
	v_lshl_add_u64 v[2:3], s[42:43], 0, v[2:3]
	v_bfe_u32 v8, v4, 16, 1
	v_lshl_add_u64 v[2:3], v[2:3], 0, v[152:153]
	v_add3_u32 v4, v4, v8, s96
	global_store_short_d16_hi v[2:3], v4, off offset:512
	v_mul_f32_e32 v4, v5, v7
	v_mul_f32_e32 v4, v130, v4
	v_bfe_u32 v5, v4, 16, 1
	v_add3_u32 v4, v4, v5, s96
	global_store_short_d16_hi v[2:3], v4, off offset:576
	v_mul_f32_e32 v4, v6, v7
	v_mul_f32_e32 v4, v129, v4
	v_bfe_u32 v5, v4, 16, 1
	v_mul_f32_e32 v0, v0, v7
	v_add3_u32 v4, v4, v5, s96
	v_mul_f32_e32 v0, v128, v0
	global_store_short_d16_hi v[2:3], v4, off offset:640
	v_bfe_u32 v4, v0, 16, 1
	v_add3_u32 v0, v0, v4, s96
	global_store_short_d16_hi v[2:3], v0, off offset:704
	v_rcp_f32_e32 v0, v1
	s_nop 0
	v_mul_f32_e32 v0, s20, v0
	s_waitcnt vmcnt(48)
	v_fma_f32 v3, -v43, v0, v81
	v_fma_f32 v2, -v59, v0, v80
	v_mul_f32_e32 v1, v3, v3
	v_fmac_f32_e32 v1, v2, v2
	v_fma_f32 v4, -v27, v0, v82
	v_fmac_f32_e32 v1, v4, v4
	v_fma_f32 v5, -v11, v0, v83
	v_fmac_f32_e32 v1, v5, v5
	ds_bpermute_b32 v0, v202, v1
	s_waitcnt lgkmcnt(0)
	v_add_f32_e32 v0, v1, v0
	ds_bpermute_b32 v1, v203, v0
	s_waitcnt lgkmcnt(0)
	v_add_f32_e32 v0, v0, v1
	ds_bpermute_b32 v1, v204, v0
	s_waitcnt lgkmcnt(0)
	v_add_f32_e32 v0, v0, v1
	ds_bpermute_b32 v1, v205, v0
	s_waitcnt lgkmcnt(0)
	v_add_f32_e32 v0, v0, v1
	ds_bpermute_b32 v1, v206, v0
	s_waitcnt lgkmcnt(0)
	v_add_f32_e32 v0, v0, v1
	v_fmamk_f32 v0, v0, 0x3c000000, v228
	v_rsq_f32_e32 v6, v0
	v_or_b32_e32 v0, 19, v124
	v_mov_b32_e32 v1, v125
	v_lshlrev_b64 v[0:1], 11, v[0:1]
	v_mul_f32_e32 v2, v2, v6
	v_mul_f32_e32 v2, v131, v2
	v_lshl_add_u64 v[0:1], s[42:43], 0, v[0:1]
	v_bfe_u32 v7, v2, 16, 1
	v_lshl_add_u64 v[0:1], v[0:1], 0, v[152:153]
	v_add3_u32 v2, v2, v7, s96
	global_store_short_d16_hi v[0:1], v2, off offset:512
	v_mul_f32_e32 v2, v3, v6
	v_mul_f32_e32 v2, v130, v2
	v_bfe_u32 v3, v2, 16, 1
	v_add3_u32 v2, v2, v3, s96
	global_store_short_d16_hi v[0:1], v2, off offset:576
	v_mul_f32_e32 v2, v4, v6
	v_mul_f32_e32 v2, v129, v2
	v_bfe_u32 v3, v2, 16, 1
	v_add3_u32 v2, v2, v3, s96
	global_store_short_d16_hi v[0:1], v2, off offset:640
	v_mul_f32_e32 v2, v5, v6
	v_mul_f32_e32 v2, v128, v2
	v_bfe_u32 v3, v2, 16, 1
	v_add3_u32 v2, v2, v3, s96
	global_store_short_d16_hi v[0:1], v2, off offset:704
	ds_read_b64 v[0:1], v240 offset:49248
	s_waitcnt lgkmcnt(0)
	v_rcp_f32_e32 v0, v0
	s_nop 0
	v_mul_f32_e32 v0, s20, v0
	s_waitcnt vmcnt(51)
	v_fma_f32 v5, -v44, v0, v77
	v_fma_f32 v4, -v60, v0, v76
	v_mul_f32_e32 v2, v5, v5
	v_fmac_f32_e32 v2, v4, v4
	v_fma_f32 v6, -v28, v0, v78
	v_fmac_f32_e32 v2, v6, v6
	v_fma_f32 v0, -v12, v0, v79
	v_fmac_f32_e32 v2, v0, v0
	ds_bpermute_b32 v3, v202, v2
	s_waitcnt lgkmcnt(0)
	v_add_f32_e32 v2, v2, v3
	ds_bpermute_b32 v3, v203, v2
	s_waitcnt lgkmcnt(0)
	v_add_f32_e32 v2, v2, v3
	ds_bpermute_b32 v3, v204, v2
	s_waitcnt lgkmcnt(0)
	v_add_f32_e32 v2, v2, v3
	ds_bpermute_b32 v3, v205, v2
	s_waitcnt lgkmcnt(0)
	v_add_f32_e32 v2, v2, v3
	ds_bpermute_b32 v3, v206, v2
	s_waitcnt lgkmcnt(0)
	v_add_f32_e32 v2, v2, v3
	v_fmamk_f32 v2, v2, 0x3c000000, v228
	v_rsq_f32_e32 v7, v2
	v_or_b32_e32 v2, 24, v124
	v_mov_b32_e32 v3, v125
	v_lshlrev_b64 v[2:3], 11, v[2:3]
	v_mul_f32_e32 v4, v4, v7
	v_mul_f32_e32 v4, v131, v4
	v_lshl_add_u64 v[2:3], s[42:43], 0, v[2:3]
	v_bfe_u32 v8, v4, 16, 1
	v_lshl_add_u64 v[2:3], v[2:3], 0, v[152:153]
	v_add3_u32 v4, v4, v8, s96
	global_store_short_d16_hi v[2:3], v4, off offset:512
	v_mul_f32_e32 v4, v5, v7
	v_mul_f32_e32 v4, v130, v4
	v_bfe_u32 v5, v4, 16, 1
	v_add3_u32 v4, v4, v5, s96
	global_store_short_d16_hi v[2:3], v4, off offset:576
	v_mul_f32_e32 v4, v6, v7
	v_mul_f32_e32 v4, v129, v4
	v_bfe_u32 v5, v4, 16, 1
	v_mul_f32_e32 v0, v0, v7
	v_add3_u32 v4, v4, v5, s96
	v_mul_f32_e32 v0, v128, v0
	global_store_short_d16_hi v[2:3], v4, off offset:640
	v_bfe_u32 v4, v0, 16, 1
	v_add3_u32 v0, v0, v4, s96
	global_store_short_d16_hi v[2:3], v0, off offset:704
	v_rcp_f32_e32 v0, v1
	s_nop 0
	v_mul_f32_e32 v0, s20, v0
	s_waitcnt vmcnt(54)
	v_fma_f32 v3, -v45, v0, v73
	v_fma_f32 v2, -v61, v0, v72
	v_mul_f32_e32 v1, v3, v3
	v_fmac_f32_e32 v1, v2, v2
	v_fma_f32 v4, -v29, v0, v74
	v_fmac_f32_e32 v1, v4, v4
	v_fma_f32 v5, -v13, v0, v75
	v_fmac_f32_e32 v1, v5, v5
	ds_bpermute_b32 v0, v202, v1
	s_waitcnt lgkmcnt(0)
	v_add_f32_e32 v0, v1, v0
	ds_bpermute_b32 v1, v203, v0
	s_waitcnt lgkmcnt(0)
	v_add_f32_e32 v0, v0, v1
	ds_bpermute_b32 v1, v204, v0
	s_waitcnt lgkmcnt(0)
	v_add_f32_e32 v0, v0, v1
	ds_bpermute_b32 v1, v205, v0
	s_waitcnt lgkmcnt(0)
	v_add_f32_e32 v0, v0, v1
	ds_bpermute_b32 v1, v206, v0
	s_waitcnt lgkmcnt(0)
	v_add_f32_e32 v0, v0, v1
	v_fmamk_f32 v0, v0, 0x3c000000, v228
	v_rsq_f32_e32 v6, v0
	v_or_b32_e32 v0, 25, v124
	v_mov_b32_e32 v1, v125
	v_lshlrev_b64 v[0:1], 11, v[0:1]
	v_mul_f32_e32 v2, v2, v6
	v_mul_f32_e32 v2, v131, v2
	v_lshl_add_u64 v[0:1], s[42:43], 0, v[0:1]
	v_bfe_u32 v7, v2, 16, 1
	v_lshl_add_u64 v[0:1], v[0:1], 0, v[152:153]
	v_add3_u32 v2, v2, v7, s96
	global_store_short_d16_hi v[0:1], v2, off offset:512
	v_mul_f32_e32 v2, v3, v6
	v_mul_f32_e32 v2, v130, v2
	v_bfe_u32 v3, v2, 16, 1
	v_add3_u32 v2, v2, v3, s96
	global_store_short_d16_hi v[0:1], v2, off offset:576
	v_mul_f32_e32 v2, v4, v6
	v_mul_f32_e32 v2, v129, v2
	v_bfe_u32 v3, v2, 16, 1
	v_add3_u32 v2, v2, v3, s96
	global_store_short_d16_hi v[0:1], v2, off offset:640
	v_mul_f32_e32 v2, v5, v6
	v_mul_f32_e32 v2, v128, v2
	v_bfe_u32 v3, v2, 16, 1
	v_add3_u32 v2, v2, v3, s96
	global_store_short_d16_hi v[0:1], v2, off offset:704
	ds_read_b64 v[0:1], v240 offset:49256
	s_waitcnt lgkmcnt(0)
	v_rcp_f32_e32 v0, v0
	s_nop 0
	v_mul_f32_e32 v0, s20, v0
	s_waitcnt vmcnt(57)
	v_fma_f32 v5, -v46, v0, v69
	v_fma_f32 v4, -v62, v0, v68
	v_mul_f32_e32 v2, v5, v5
	v_fmac_f32_e32 v2, v4, v4
	v_fma_f32 v6, -v30, v0, v70
	v_fmac_f32_e32 v2, v6, v6
	v_fma_f32 v0, -v14, v0, v71
	v_fmac_f32_e32 v2, v0, v0
	ds_bpermute_b32 v3, v202, v2
	s_waitcnt lgkmcnt(0)
	v_add_f32_e32 v2, v2, v3
	ds_bpermute_b32 v3, v203, v2
	s_waitcnt lgkmcnt(0)
	v_add_f32_e32 v2, v2, v3
	ds_bpermute_b32 v3, v204, v2
	s_waitcnt lgkmcnt(0)
	v_add_f32_e32 v2, v2, v3
	ds_bpermute_b32 v3, v205, v2
	s_waitcnt lgkmcnt(0)
	v_add_f32_e32 v2, v2, v3
	ds_bpermute_b32 v3, v206, v2
	s_waitcnt lgkmcnt(0)
	v_add_f32_e32 v2, v2, v3
	v_fmamk_f32 v2, v2, 0x3c000000, v228
	v_rsq_f32_e32 v7, v2
	v_or_b32_e32 v2, 26, v124
	v_mov_b32_e32 v3, v125
	v_lshlrev_b64 v[2:3], 11, v[2:3]
	v_mul_f32_e32 v4, v4, v7
	v_mul_f32_e32 v4, v131, v4
	v_lshl_add_u64 v[2:3], s[42:43], 0, v[2:3]
	v_bfe_u32 v8, v4, 16, 1
	v_lshl_add_u64 v[2:3], v[2:3], 0, v[152:153]
	v_add3_u32 v4, v4, v8, s96
	global_store_short_d16_hi v[2:3], v4, off offset:512
	v_mul_f32_e32 v4, v5, v7
	v_mul_f32_e32 v4, v130, v4
	v_bfe_u32 v5, v4, 16, 1
	v_add3_u32 v4, v4, v5, s96
	global_store_short_d16_hi v[2:3], v4, off offset:576
	v_mul_f32_e32 v4, v6, v7
	v_mul_f32_e32 v4, v129, v4
	v_bfe_u32 v5, v4, 16, 1
	v_mul_f32_e32 v0, v0, v7
	v_add3_u32 v4, v4, v5, s96
	v_mul_f32_e32 v0, v128, v0
	global_store_short_d16_hi v[2:3], v4, off offset:640
	v_bfe_u32 v4, v0, 16, 1
	v_add3_u32 v0, v0, v4, s96
	global_store_short_d16_hi v[2:3], v0, off offset:704
	v_rcp_f32_e32 v0, v1
	v_or_b32_e32 v124, 27, v124
	v_mul_f32_e32 v0, s20, v0
	s_waitcnt vmcnt(60)
	v_fma_f32 v3, -v47, v0, v65
	v_fma_f32 v2, -v63, v0, v64
	v_mul_f32_e32 v1, v3, v3
	v_fmac_f32_e32 v1, v2, v2
	v_fma_f32 v4, -v31, v0, v66
	v_fmac_f32_e32 v1, v4, v4
	v_fma_f32 v5, -v15, v0, v67
	v_fmac_f32_e32 v1, v5, v5
	ds_bpermute_b32 v0, v202, v1
	s_waitcnt lgkmcnt(0)
	v_add_f32_e32 v0, v1, v0
	ds_bpermute_b32 v1, v203, v0
	s_waitcnt lgkmcnt(0)
	v_add_f32_e32 v0, v0, v1
	ds_bpermute_b32 v1, v204, v0
	s_waitcnt lgkmcnt(0)
	v_add_f32_e32 v0, v0, v1
	ds_bpermute_b32 v1, v205, v0
	s_waitcnt lgkmcnt(0)
	v_add_f32_e32 v0, v0, v1
	ds_bpermute_b32 v1, v206, v0
	s_waitcnt lgkmcnt(0)
	v_add_f32_e32 v0, v0, v1
	v_fmamk_f32 v0, v0, 0x3c000000, v228
	v_rsq_f32_e32 v6, v0
	v_lshlrev_b64 v[0:1], 11, v[124:125]
	v_lshl_add_u64 v[0:1], s[42:43], 0, v[0:1]
	v_lshl_add_u64 v[0:1], v[0:1], 0, v[152:153]
	v_mul_f32_e32 v2, v2, v6
	v_mul_f32_e32 v2, v131, v2
	v_bfe_u32 v7, v2, 16, 1
	v_add3_u32 v2, v2, v7, s96
	global_store_short_d16_hi v[0:1], v2, off offset:512
	v_mul_f32_e32 v2, v3, v6
	v_mul_f32_e32 v2, v130, v2
	v_bfe_u32 v3, v2, 16, 1
	v_add3_u32 v2, v2, v3, s96
	global_store_short_d16_hi v[0:1], v2, off offset:576
	v_mul_f32_e32 v2, v4, v6
	v_mul_f32_e32 v2, v129, v2
	v_bfe_u32 v3, v2, 16, 1
	v_add3_u32 v2, v2, v3, s96
	global_store_short_d16_hi v[0:1], v2, off offset:640
	v_mul_f32_e32 v2, v5, v6
	v_mul_f32_e32 v2, v128, v2
	v_bfe_u32 v3, v2, 16, 1
	v_add3_u32 v2, v2, v3, s96
	global_store_short_d16_hi v[0:1], v2, off offset:704
	s_waitcnt vmcnt(63) expcnt(7) lgkmcnt(15)
	s_barrier
	s_cbranch_vccnz .LBB0_869
